# rowstat partials with v_dot2c_f32_bf16 (bf16 pairs of the rounded residual, f32 accumulate) in the AddRes epilogues: ~100 instead of 273 added instructions per unit
# speedup vs baseline: 1.0019x; 1.0009x over previous
; #define PG8_STAGE(bufoff, gbase, voff) do { _Pragma("unroll") for (int _i = 0; _i < 2; ++_i) \
;         __builtin_amdgcn_global_load_lds((const unsigned*)((const char*)(gbase) + (voff)[_i]), (LAS unsigned*)(lds + (bufoff) + ldsw + _i * 8192), 16, 0, 0); } while (0)
; #define PG8_LDA(dst, b, h) do { _Pragma("unroll") for (int m = 0; m < 4; ++m) _Pragma("unroll") for (int k = 0; k < 2; ++k) dst[m][k] = *(const LAS bf16x8*)(lds + PG8_SA(b, h) + aoff + m * 2048 + k * 1024); } while (0)
; #define PG8_LDB(dst, b, h) do { _Pragma("unroll") for (int n = 0; n < 2; ++n) _Pragma("unroll") for (int k = 0; k < 2; ++k) dst[n][k] = *(const LAS bf16x8*)(lds + PG8_SB(b, h) + boff + n * 2048 + k * 1024); } while (0)
; #define PG8_MMA(ai, bj, At, Bt) do { __builtin_amdgcn_s_setprio(1); _Pragma("unroll") for (int m = 0; m < 4; ++m) _Pragma("unroll") for (int n = 0; n < 2; ++n) _Pragma("unroll") for (int k = 0; k < 2; ++k) \
;         acc[ai][bj][m][n] = __builtin_amdgcn_mfma_f32_16x16x32_bf16(Bt[n][k], At[m][k], acc[ai][bj][m][n], 0, 0, 0); __builtin_amdgcn_s_setprio(0); } while (0)
; #define PG8_WAIT_V(n) asm volatile("s_waitcnt vmcnt(" #n ")" ::: "memory")
; #define PG8_WAIT_L(n) asm volatile("s_waitcnt lgkmcnt(" #n ")" ::: "memory")
; #define PG8_BAR __builtin_amdgcn_s_barrier()
; #define PG8_SCHED __builtin_amdgcn_sched_barrier(0)
; template <class Epi, class Sched>
; __device__ __forceinline__ void gemm_phase(LAS unsigned char* lds, const Gemm g, const Sched& S, const Epi& E) {
;     ...
;             PG8_LDB(B0, 0, 0); PG8_SCHED; PG8_LDA(At, 0, 0); PG8_STAGE(PG8_SA(1, 1), a1 + hstepA, voffA);
;             PG8_WAIT_L(8); PG8_BAR; PG8_WAIT_L(0); PG8_MMA(0, 0, At, B0); PG8_BAR; PG8_SCHED;
;             PG8_LDB(B1, 0, 1); PG8_STAGE(PG8_SB(0, 0), b2, voffB);
;             PG8_BAR; PG8_WAIT_L(0); PG8_MMA(0, 1, At, B1); PG8_BAR;
;             PG8_LDA(At, 0, 1); PG8_STAGE(PG8_SA(0, 0), a2, voffA);
;             PG8_BAR; PG8_WAIT_L(0); PG8_MMA(1, 0, At, B0); PG8_BAR; PG8_SCHED;
;             PG8_STAGE(PG8_SB(0, 1), b2 + hstepB, voffB);
;             PG8_WAIT_V(6); PG8_BAR; PG8_MMA(1, 1, At, B1); PG8_BAR;
.LBB0_966:
	s_setprio 0
	s_add_u32 s20, s6, 0xfff80080
	s_addc_u32 s21, s7, -1
	s_add_i32 s52, 0, 0x10000
	v_add_u32_e32 v144, s52, v1
	ds_read_b128 v[132:135], v144
	ds_read_b128 v[136:139], v144 offset:1024
	ds_read_b128 v[140:143], v144 offset:2048
	ds_read_b128 v[144:147], v144 offset:3072
	s_cmp_eq_u32 s51, 28
	s_cselect_b32 s25, s15, s21
	s_cselect_b32 s24, s47, s20
	s_cselect_b32 s21, s1, s50
	s_cselect_b32 s20, s48, s49
	ds_read_b128 v[148:151], v224
	ds_read_b128 v[152:155], v224 offset:1024
	ds_read_b128 v[156:159], v224 offset:2048
	ds_read_b128 v[160:163], v224 offset:3072
	ds_read_b128 v[164:167], v224 offset:4096
	ds_read_b128 v[168:171], v224 offset:5120
	ds_read_b128 v[172:175], v224 offset:6144
	ds_read_b128 v[176:179], v224 offset:7168
	s_add_i32 s54, 0, 0x14000
	v_add_u32_e32 v202, s54, v1
	ds_read_b128 v[180:183], v202
	ds_read_b128 v[184:187], v202 offset:1024
	ds_read_b128 v[188:191], v202 offset:2048
	ds_read_b128 v[202:205], v202 offset:3072
	s_add_i32 m0, s31, 0xc000
	s_nop 0
	global_load_lds_dwordx4 v198, s[6:7]
	s_add_i32 m0, s31, 0xe000
	s_nop 0
	global_load_lds_dwordx4 v200, s[6:7]
	s_waitcnt lgkmcnt(0)
	s_setprio 1
	s_barrier
	v_mfma_f32_16x16x32_bf16 v[128:131], v[132:135], v[148:151], v[128:131]
	v_mfma_f32_16x16x32_bf16 v[124:127], v[140:143], v[148:151], v[124:127]
	v_mfma_f32_16x16x32_bf16 v[112:115], v[132:135], v[156:159], v[112:115]
	v_mfma_f32_16x16x32_bf16 v[108:111], v[140:143], v[156:159], v[108:111]
	v_mfma_f32_16x16x32_bf16 v[100:103], v[132:135], v[164:167], v[100:103]
	v_mfma_f32_16x16x32_bf16 v[92:95], v[140:143], v[164:167], v[92:95]
	v_mfma_f32_16x16x32_bf16 v[84:87], v[132:135], v[172:175], v[84:87]
	v_mfma_f32_16x16x32_bf16 v[76:79], v[140:143], v[172:175], v[76:79]
	v_mfma_f32_16x16x32_bf16 v[128:131], v[136:139], v[152:155], v[128:131]
	v_mfma_f32_16x16x32_bf16 v[124:127], v[144:147], v[152:155], v[124:127]
	v_mfma_f32_16x16x32_bf16 v[112:115], v[136:139], v[160:163], v[112:115]
	v_mfma_f32_16x16x32_bf16 v[108:111], v[144:147], v[160:163], v[108:111]
	v_mfma_f32_16x16x32_bf16 v[100:103], v[136:139], v[168:171], v[100:103]
	v_mfma_f32_16x16x32_bf16 v[92:95], v[144:147], v[168:171], v[92:95]
	v_mfma_f32_16x16x32_bf16 v[84:87], v[136:139], v[176:179], v[84:87]
	v_mfma_f32_16x16x32_bf16 v[76:79], v[144:147], v[176:179], v[76:79]
	v_mfma_f32_16x16x32_bf16 v[120:123], v[180:183], v[148:151], v[120:123]
	v_mfma_f32_16x16x32_bf16 v[116:119], v[188:191], v[148:151], v[116:119]
	v_mfma_f32_16x16x32_bf16 v[104:107], v[180:183], v[156:159], v[104:107]
	v_mfma_f32_16x16x32_bf16 v[96:99], v[188:191], v[156:159], v[96:99]
	v_mfma_f32_16x16x32_bf16 v[88:91], v[180:183], v[164:167], v[88:91]
	v_mfma_f32_16x16x32_bf16 v[80:83], v[188:191], v[164:167], v[80:83]
	v_mfma_f32_16x16x32_bf16 v[72:75], v[180:183], v[172:175], v[72:75]
	v_mfma_f32_16x16x32_bf16 v[68:71], v[188:191], v[172:175], v[68:71]
	v_mfma_f32_16x16x32_bf16 v[120:123], v[184:187], v[152:155], v[120:123]
	v_mfma_f32_16x16x32_bf16 v[116:119], v[202:205], v[152:155], v[116:119]
	v_mfma_f32_16x16x32_bf16 v[104:107], v[184:187], v[160:163], v[104:107]
	v_mfma_f32_16x16x32_bf16 v[96:99], v[202:205], v[160:163], v[96:99]
	v_mfma_f32_16x16x32_bf16 v[88:91], v[184:187], v[168:171], v[88:91]
	v_mfma_f32_16x16x32_bf16 v[80:83], v[202:205], v[168:171], v[80:83]
	v_mfma_f32_16x16x32_bf16 v[72:75], v[184:187], v[176:179], v[72:75]
	v_mfma_f32_16x16x32_bf16 v[68:71], v[202:205], v[176:179], v[68:71]
	s_barrier
	s_setprio 0
	ds_read_b128 v[148:151], v224 offset:16384
	ds_read_b128 v[152:155], v224 offset:17408
	ds_read_b128 v[156:159], v224 offset:18432
	ds_read_b128 v[160:163], v224 offset:19456
	ds_read_b128 v[164:167], v224 offset:20480
	ds_read_b128 v[168:171], v224 offset:21504
	ds_read_b128 v[172:175], v224 offset:22528
	ds_read_b128 v[176:179], v224 offset:23552
	s_add_i32 s52, s52, s30
	v_lshl_add_u64 v[206:207], s[20:21], 0, v[2:3]
	s_mov_b32 m0, s52
	s_nop 0
	global_load_lds_dwordx4 v[206:207], off
	v_lshl_add_u64 v[208:209], s[20:21], 0, v[192:193]
	s_add_i32 m0, s52, 0x2000
	s_nop 0
	global_load_lds_dwordx4 v[208:209], off
	s_mov_b32 m0, s31
	v_lshl_add_u64 v[210:211], s[24:25], 0, v[196:197]
	global_load_lds_dwordx4 v[210:211], off
	v_lshl_add_u64 v[212:213], s[24:25], 0, v[194:195]
	s_mov_b32 m0, s35
	s_nop 0
	global_load_lds_dwordx4 v[212:213], off
	s_add_u32 s52, s20, 0x80000
	s_addc_u32 s53, s21, 0
	s_add_i32 s54, s54, s30
	s_mov_b32 m0, s54
	s_nop 0
	global_load_lds_dwordx4 v2, s[52:53]
	s_add_i32 m0, s54, 0x2000
	s_nop 0
	global_load_lds_dwordx4 v192, s[52:53]
	s_waitcnt lgkmcnt(0)
	s_waitcnt vmcnt(6)
	s_setprio 1
	s_barrier
; #define PG8_STAGE(bufoff, gbase, voff) do { _Pragma("unroll") for (int _i = 0; _i < 2; ++_i) \
;         __builtin_amdgcn_global_load_lds((const unsigned*)((const char*)(gbase) + (voff)[_i]), (LAS unsigned*)(lds + (bufoff) + ldsw + _i * 8192), 16, 0, 0); } while (0)
; #define PG8_LDA(dst, b, h) do { _Pragma("unroll") for (int m = 0; m < 4; ++m) _Pragma("unroll") for (int k = 0; k < 2; ++k) dst[m][k] = *(const LAS bf16x8*)(lds + PG8_SA(b, h) + aoff + m * 2048 + k * 1024); } while (0)
; #define PG8_LDB(dst, b, h) do { _Pragma("unroll") for (int n = 0; n < 2; ++n) _Pragma("unroll") for (int k = 0; k < 2; ++k) dst[n][k] = *(const LAS bf16x8*)(lds + PG8_SB(b, h) + boff + n * 2048 + k * 1024); } while (0)
; #define PG8_MMA(ai, bj, At, Bt) do { __builtin_amdgcn_s_setprio(1); _Pragma("unroll") for (int m = 0; m < 4; ++m) _Pragma("unroll") for (int n = 0; n < 2; ++n) _Pragma("unroll") for (int k = 0; k < 2; ++k) \
;         acc[ai][bj][m][n] = __builtin_amdgcn_mfma_f32_16x16x32_bf16(Bt[n][k], At[m][k], acc[ai][bj][m][n], 0, 0, 0); __builtin_amdgcn_s_setprio(0); } while (0)
; #define PG8_WAIT_V(n) asm volatile("s_waitcnt vmcnt(" #n ")" ::: "memory")
; #define PG8_WAIT_L(n) asm volatile("s_waitcnt lgkmcnt(" #n ")" ::: "memory")
; #define PG8_BAR __builtin_amdgcn_s_barrier()
; #define PG8_SCHED __builtin_amdgcn_sched_barrier(0)
; template <class Epi, class Sched>
; __device__ __forceinline__ void gemm_phase(LAS unsigned char* lds, const Gemm g, const Sched& S, const Epi& E) {
;     ...
;             PG8_BAR; PG8_WAIT_L(0); PG8_MMA(1, 0, At, B0); PG8_BAR; PG8_SCHED;
;             PG8_STAGE(PG8_SB(0, 1), b2 + hstepB, voffB);
;             PG8_WAIT_V(6); PG8_BAR; PG8_MMA(1, 1, At, B1); PG8_BAR;
;             PG8_LDB(B0, 1, 0); PG8_SCHED; PG8_LDA(At, 1, 0); PG8_STAGE(PG8_SA(0, 1), a2 + hstepA, voffA);
;             PG8_WAIT_L(8); PG8_BAR; PG8_WAIT_L(0); PG8_MMA(0, 0, At, B0); PG8_BAR; PG8_SCHED;
;             PG8_LDB(B1, 1, 1); PG8_STAGE(PG8_SB(1, 0), b3, voffB);
;             PG8_BAR; PG8_WAIT_L(0); PG8_MMA(0, 1, At, B1); PG8_BAR;
;             PG8_LDA(At, 1, 1); PG8_STAGE(PG8_SA(1, 0), a3, voffA);
;             PG8_BAR; PG8_WAIT_L(0); PG8_MMA(1, 0, At, B0); PG8_BAR; PG8_SCHED;
	v_mfma_f32_16x16x32_bf16 v[64:67], v[132:135], v[148:151], v[64:67]
	v_mfma_f32_16x16x32_bf16 v[60:63], v[140:143], v[148:151], v[60:63]
	v_mfma_f32_16x16x32_bf16 v[52:55], v[132:135], v[156:159], v[52:55]
	v_mfma_f32_16x16x32_bf16 v[44:47], v[140:143], v[156:159], v[44:47]
	v_mfma_f32_16x16x32_bf16 v[36:39], v[132:135], v[164:167], v[36:39]
	v_mfma_f32_16x16x32_bf16 v[28:31], v[140:143], v[164:167], v[28:31]
	v_mfma_f32_16x16x32_bf16 v[20:23], v[132:135], v[172:175], v[20:23]
	v_mfma_f32_16x16x32_bf16 v[12:15], v[140:143], v[172:175], v[12:15]
	v_mfma_f32_16x16x32_bf16 v[64:67], v[136:139], v[152:155], v[64:67]
	v_mfma_f32_16x16x32_bf16 v[60:63], v[144:147], v[152:155], v[60:63]
	v_mfma_f32_16x16x32_bf16 v[52:55], v[136:139], v[160:163], v[52:55]
	v_mfma_f32_16x16x32_bf16 v[44:47], v[144:147], v[160:163], v[44:47]
	v_mfma_f32_16x16x32_bf16 v[36:39], v[136:139], v[168:171], v[36:39]
	v_mfma_f32_16x16x32_bf16 v[28:31], v[144:147], v[168:171], v[28:31]
	v_mfma_f32_16x16x32_bf16 v[20:23], v[136:139], v[176:179], v[20:23]
	v_mfma_f32_16x16x32_bf16 v[12:15], v[144:147], v[176:179], v[12:15]
	v_mfma_f32_16x16x32_bf16 v[56:59], v[180:183], v[148:151], v[56:59]
	v_mfma_f32_16x16x32_bf16 v[48:51], v[188:191], v[148:151], v[48:51]
	v_mfma_f32_16x16x32_bf16 v[40:43], v[180:183], v[156:159], v[40:43]
	v_mfma_f32_16x16x32_bf16 v[32:35], v[188:191], v[156:159], v[32:35]
	v_mfma_f32_16x16x32_bf16 v[24:27], v[180:183], v[164:167], v[24:27]
	v_mfma_f32_16x16x32_bf16 v[16:19], v[188:191], v[164:167], v[16:19]
	v_mfma_f32_16x16x32_bf16 v[8:11], v[180:183], v[172:175], v[8:11]
	v_mfma_f32_16x16x32_bf16 v[4:7], v[188:191], v[172:175], v[4:7]
	v_mfma_f32_16x16x32_bf16 v[56:59], v[184:187], v[152:155], v[56:59]
	v_mfma_f32_16x16x32_bf16 v[48:51], v[202:205], v[152:155], v[48:51]
	v_mfma_f32_16x16x32_bf16 v[40:43], v[184:187], v[160:163], v[40:43]
	v_mfma_f32_16x16x32_bf16 v[32:35], v[202:205], v[160:163], v[32:35]
	v_mfma_f32_16x16x32_bf16 v[24:27], v[184:187], v[168:171], v[24:27]
	v_mfma_f32_16x16x32_bf16 v[16:19], v[202:205], v[168:171], v[16:19]
	v_mfma_f32_16x16x32_bf16 v[8:11], v[184:187], v[176:179], v[8:11]
	v_mfma_f32_16x16x32_bf16 v[4:7], v[202:205], v[176:179], v[4:7]
	s_barrier
	s_setprio 0
	s_add_i32 s52, 0, 0x18000
	v_add_u32_e32 v144, s52, v1
	ds_read_b128 v[132:135], v144
	ds_read_b128 v[136:139], v144 offset:1024
	ds_read_b128 v[140:143], v144 offset:2048
	ds_read_b128 v[144:147], v144 offset:3072
	s_add_u32 s24, s24, 0x80000
	s_addc_u32 s25, s25, 0
	ds_read_b128 v[148:151], v224 offset:32768
	ds_read_b128 v[152:155], v224 offset:33792
	ds_read_b128 v[156:159], v224 offset:34816
	ds_read_b128 v[160:163], v224 offset:35840
	ds_read_b128 v[164:167], v224 offset:36864
	ds_read_b128 v[168:171], v224 offset:37888
	ds_read_b128 v[172:175], v224 offset:38912
	ds_read_b128 v[176:179], v224 offset:39936
	s_mov_b32 m0, s36
	s_nop 0
	global_load_lds_dwordx4 v196, s[24:25]
	s_mov_b32 m0, s37
	s_nop 0
	global_load_lds_dwordx4 v194, s[24:25]
	s_add_i32 s24, 0, 0x1c000
	v_add_u32_e32 v202, s24, v1
	ds_read_b128 v[180:183], v202
	ds_read_b128 v[184:187], v202 offset:1024
	ds_read_b128 v[188:191], v202 offset:2048
	ds_read_b128 v[202:205], v202 offset:3072
	s_waitcnt lgkmcnt(0)
	s_setprio 1
	s_barrier
	v_mfma_f32_16x16x32_bf16 v[128:131], v[132:135], v[148:151], v[128:131]
	v_mfma_f32_16x16x32_bf16 v[124:127], v[140:143], v[148:151], v[124:127]
	v_mfma_f32_16x16x32_bf16 v[112:115], v[132:135], v[156:159], v[112:115]
	v_mfma_f32_16x16x32_bf16 v[108:111], v[140:143], v[156:159], v[108:111]
	v_mfma_f32_16x16x32_bf16 v[100:103], v[132:135], v[164:167], v[100:103]
	v_mfma_f32_16x16x32_bf16 v[92:95], v[140:143], v[164:167], v[92:95]
	v_mfma_f32_16x16x32_bf16 v[84:87], v[132:135], v[172:175], v[84:87]
	v_mfma_f32_16x16x32_bf16 v[76:79], v[140:143], v[172:175], v[76:79]
	v_mfma_f32_16x16x32_bf16 v[128:131], v[136:139], v[152:155], v[128:131]
	v_mfma_f32_16x16x32_bf16 v[124:127], v[144:147], v[152:155], v[124:127]
	v_mfma_f32_16x16x32_bf16 v[112:115], v[136:139], v[160:163], v[112:115]
	v_mfma_f32_16x16x32_bf16 v[108:111], v[144:147], v[160:163], v[108:111]
	v_mfma_f32_16x16x32_bf16 v[100:103], v[136:139], v[168:171], v[100:103]
	v_mfma_f32_16x16x32_bf16 v[92:95], v[144:147], v[168:171], v[92:95]
	v_mfma_f32_16x16x32_bf16 v[84:87], v[136:139], v[176:179], v[84:87]
	v_mfma_f32_16x16x32_bf16 v[76:79], v[144:147], v[176:179], v[76:79]
	v_mfma_f32_16x16x32_bf16 v[120:123], v[180:183], v[148:151], v[120:123]
	v_mfma_f32_16x16x32_bf16 v[116:119], v[188:191], v[148:151], v[116:119]
	v_mfma_f32_16x16x32_bf16 v[104:107], v[180:183], v[156:159], v[104:107]
	v_mfma_f32_16x16x32_bf16 v[96:99], v[188:191], v[156:159], v[96:99]
	v_mfma_f32_16x16x32_bf16 v[88:91], v[180:183], v[164:167], v[88:91]
	v_mfma_f32_16x16x32_bf16 v[80:83], v[188:191], v[164:167], v[80:83]
	v_mfma_f32_16x16x32_bf16 v[72:75], v[180:183], v[172:175], v[72:75]
	v_mfma_f32_16x16x32_bf16 v[68:71], v[188:191], v[172:175], v[68:71]
	v_mfma_f32_16x16x32_bf16 v[120:123], v[184:187], v[152:155], v[120:123]
	v_mfma_f32_16x16x32_bf16 v[116:119], v[202:205], v[152:155], v[116:119]
	v_mfma_f32_16x16x32_bf16 v[104:107], v[184:187], v[160:163], v[104:107]
	v_mfma_f32_16x16x32_bf16 v[96:99], v[202:205], v[160:163], v[96:99]
	v_mfma_f32_16x16x32_bf16 v[88:91], v[184:187], v[168:171], v[88:91]
	v_mfma_f32_16x16x32_bf16 v[80:83], v[202:205], v[168:171], v[80:83]
	v_mfma_f32_16x16x32_bf16 v[72:75], v[184:187], v[176:179], v[72:75]
	v_mfma_f32_16x16x32_bf16 v[68:71], v[202:205], v[176:179], v[68:71]
	s_barrier
; #define PG8_STAGE(bufoff, gbase, voff) do { _Pragma("unroll") for (int _i = 0; _i < 2; ++_i) \
;         __builtin_amdgcn_global_load_lds((const unsigned*)((const char*)(gbase) + (voff)[_i]), (LAS unsigned*)(lds + (bufoff) + ldsw + _i * 8192), 16, 0, 0); } while (0)
; #define PG8_MMA(ai, bj, At, Bt) do { __builtin_amdgcn_s_setprio(1); _Pragma("unroll") for (int m = 0; m < 4; ++m) _Pragma("unroll") for (int n = 0; n < 2; ++n) _Pragma("unroll") for (int k = 0; k < 2; ++k) \
;         acc[ai][bj][m][n] = __builtin_amdgcn_mfma_f32_16x16x32_bf16(Bt[n][k], At[m][k], acc[ai][bj][m][n], 0, 0, 0); __builtin_amdgcn_s_setprio(0); } while (0)
; #define PG8_WAIT_V(n) asm volatile("s_waitcnt vmcnt(" #n ")" ::: "memory")
; #define PG8_WAIT_L(n) asm volatile("s_waitcnt lgkmcnt(" #n ")" ::: "memory")
; #define PG8_BAR __builtin_amdgcn_s_barrier()
; #define PG8_SCHED __builtin_amdgcn_sched_barrier(0)
;     __device__ __forceinline__ void operator()(const f32x4 (&acc)[2][2][4][2], const Unit& u, int wr, int wc, int, int) const {
;     ...
;         u32x4 cin[2][4][2];
; #pragma unroll
;         for (int ai = 0; ai < 2; ++ai)
; #pragma unroll
;             for (int m = 0; m < 4; ++m)
; #pragma unroll
;                 for (int bj = 0; bj < 2; ++bj) cin[ai][m][bj] = *(const u32x4*)(C + (size_t)(row0 + ai * HALF + m * 16) * ldc + col0 + bj * HALF);
; template <class Epi, class Sched>
; __device__ __forceinline__ void gemm_phase(LAS unsigned char* lds, const Gemm g, const Sched& S, const Epi& E) {
;     ...
;             PG8_BAR; PG8_WAIT_L(0); PG8_MMA(1, 0, At, B0); PG8_BAR; PG8_SCHED;
;             PG8_STAGE(PG8_SB(1, 1), b3 + hstepB, voffB);
;             PG8_WAIT_V(6); PG8_BAR; PG8_MMA(1, 1, At, B1); PG8_BAR;
	s_setprio 0
	ds_read_b128 v[148:151], v224 offset:49152
	ds_read_b128 v[152:155], v224 offset:50176
	ds_read_b128 v[156:159], v224 offset:51200
	ds_read_b128 v[160:163], v224 offset:52224
	ds_read_b128 v[164:167], v224 offset:53248
	ds_read_b128 v[168:171], v224 offset:54272
	ds_read_b128 v[172:175], v224 offset:55296
	ds_read_b128 v[176:179], v224 offset:56320
	s_add_i32 s25, s52, s30
	v_lshl_add_u64 v[206:207], v[206:207], 0, s[8:9]
	s_mov_b32 m0, s25
	s_nop 0
	global_load_lds_dwordx4 v[206:207], off
	v_lshl_add_u64 v[206:207], v[208:209], 0, s[8:9]
	s_add_i32 m0, s25, 0x2000
	s_nop 0
	global_load_lds_dwordx4 v[206:207], off
	s_mov_b32 m0, s40
	v_lshl_add_u64 v[206:207], v[210:211], 0, s[8:9]
	global_load_lds_dwordx4 v[206:207], off
	v_lshl_add_u64 v[206:207], v[212:213], 0, s[8:9]
	s_mov_b32 m0, s41
	s_nop 0
	global_load_lds_dwordx4 v[206:207], off
	s_add_u32 s20, s20, 0x80080
	s_addc_u32 s21, s21, 0
	s_add_i32 s24, s24, s30
	s_mov_b32 m0, s24
	s_nop 0
	global_load_lds_dwordx4 v2, s[20:21]
	s_add_i32 m0, s24, 0x2000
	s_nop 0
	global_load_lds_dwordx4 v192, s[20:21]
	s_add_i32 s51, s51, 2
	s_add_u32 s6, s6, 0x100
	s_addc_u32 s7, s7, 0
	s_add_u32 s49, s49, 0x100
	s_addc_u32 s50, s50, 0
	s_cmp_gt_u32 s51, 29
	s_waitcnt lgkmcnt(0)
	s_waitcnt vmcnt(6)
	s_setprio 1
	s_barrier
	v_mfma_f32_16x16x32_bf16 v[64:67], v[132:135], v[148:151], v[64:67]
	v_mfma_f32_16x16x32_bf16 v[60:63], v[140:143], v[148:151], v[60:63]
	v_mfma_f32_16x16x32_bf16 v[52:55], v[132:135], v[156:159], v[52:55]
	v_mfma_f32_16x16x32_bf16 v[44:47], v[140:143], v[156:159], v[44:47]
	v_mfma_f32_16x16x32_bf16 v[36:39], v[132:135], v[164:167], v[36:39]
	v_mfma_f32_16x16x32_bf16 v[28:31], v[140:143], v[164:167], v[28:31]
	v_mfma_f32_16x16x32_bf16 v[20:23], v[132:135], v[172:175], v[20:23]
	v_mfma_f32_16x16x32_bf16 v[12:15], v[140:143], v[172:175], v[12:15]
	v_mfma_f32_16x16x32_bf16 v[64:67], v[136:139], v[152:155], v[64:67]
	v_mfma_f32_16x16x32_bf16 v[60:63], v[144:147], v[152:155], v[60:63]
	v_mfma_f32_16x16x32_bf16 v[52:55], v[136:139], v[160:163], v[52:55]
	v_mfma_f32_16x16x32_bf16 v[44:47], v[144:147], v[160:163], v[44:47]
	v_mfma_f32_16x16x32_bf16 v[36:39], v[136:139], v[168:171], v[36:39]
	v_mfma_f32_16x16x32_bf16 v[28:31], v[144:147], v[168:171], v[28:31]
	v_mfma_f32_16x16x32_bf16 v[20:23], v[136:139], v[176:179], v[20:23]
	v_mfma_f32_16x16x32_bf16 v[12:15], v[144:147], v[176:179], v[12:15]
	v_mfma_f32_16x16x32_bf16 v[56:59], v[180:183], v[148:151], v[56:59]
	v_mfma_f32_16x16x32_bf16 v[48:51], v[188:191], v[148:151], v[48:51]
	v_mfma_f32_16x16x32_bf16 v[40:43], v[180:183], v[156:159], v[40:43]
	v_mfma_f32_16x16x32_bf16 v[32:35], v[188:191], v[156:159], v[32:35]
	v_mfma_f32_16x16x32_bf16 v[24:27], v[180:183], v[164:167], v[24:27]
	v_mfma_f32_16x16x32_bf16 v[16:19], v[188:191], v[164:167], v[16:19]
	v_mfma_f32_16x16x32_bf16 v[8:11], v[180:183], v[172:175], v[8:11]
	v_mfma_f32_16x16x32_bf16 v[4:7], v[188:191], v[172:175], v[4:7]
	v_mfma_f32_16x16x32_bf16 v[56:59], v[184:187], v[152:155], v[56:59]
	v_mfma_f32_16x16x32_bf16 v[48:51], v[202:205], v[152:155], v[48:51]
	v_mfma_f32_16x16x32_bf16 v[40:43], v[184:187], v[160:163], v[40:43]
	v_mfma_f32_16x16x32_bf16 v[32:35], v[202:205], v[160:163], v[32:35]
	v_mfma_f32_16x16x32_bf16 v[24:27], v[184:187], v[168:171], v[24:27]
	v_mfma_f32_16x16x32_bf16 v[16:19], v[202:205], v[168:171], v[16:19]
	v_mfma_f32_16x16x32_bf16 v[8:11], v[184:187], v[176:179], v[8:11]
	v_mfma_f32_16x16x32_bf16 v[4:7], v[202:205], v[176:179], v[4:7]
	s_barrier
	s_cbranch_scc0 .LBB0_966
	s_setprio 0
	v_mov_b32_e32 v133, v0
	s_lshl_b32 s1, s46, 8
	s_add_i32 s1, s1, s38
	v_and_or_b32 v132, v133, 15, s1
	s_lshl_b32 s1, s45, 8
	v_lshrrev_b32_e32 v133, 1, v133
	v_and_or_b32 v133, v133, 24, s1
	v_or_b32_e32 v134, s39, v133
	v_ashrrev_i32_e32 v135, 31, v134
	v_lshlrev_b64 v[202:203], 1, v[134:135]
	v_ashrrev_i32_e32 v133, 31, v132
	v_lshl_add_u64 v[134:135], s[88:89], 0, v[202:203]
	v_lshlrev_b64 v[226:227], 12, v[132:133]
	v_lshl_add_u64 v[136:137], v[134:135], 0, v[226:227]
	global_load_dwordx4 v[216:219], v[136:137], off
	global_load_dwordx4 v[188:191], v[136:137], off offset:256
	v_or_b32_e32 v136, 16, v132
	v_ashrrev_i32_e32 v137, 31, v136
	v_lshlrev_b64 v[222:223], 12, v[136:137]
	v_lshl_add_u64 v[136:137], v[134:135], 0, v[222:223]
	global_load_dwordx4 v[184:187], v[136:137], off
	global_load_dwordx4 v[180:183], v[136:137], off offset:256
	v_or_b32_e32 v136, 32, v132
	v_ashrrev_i32_e32 v137, 31, v136
	v_lshlrev_b64 v[220:221], 12, v[136:137]
	v_lshl_add_u64 v[136:137], v[134:135], 0, v[220:221]
	global_load_dwordx4 v[176:179], v[136:137], off
	global_load_dwordx4 v[168:171], v[136:137], off offset:256
	v_or_b32_e32 v132, 48, v132
	v_ashrrev_i32_e32 v133, 31, v132
	v_lshlrev_b64 v[212:213], 12, v[132:133]
	v_lshl_add_u64 v[132:133], v[134:135], 0, v[212:213]
	global_load_dwordx4 v[172:175], v[132:133], off
	global_load_dwordx4 v[164:167], v[132:133], off offset:256
	s_mov_b64 s[6:7], 0x80000
	v_lshl_add_u64 v[210:211], v[226:227], 0, s[6:7]
	v_lshl_add_u64 v[132:133], v[134:135], 0, v[210:211]
	global_load_dwordx4 v[160:163], v[132:133], off
	global_load_dwordx4 v[156:159], v[132:133], off offset:256
	s_mov_b64 s[6:7], 0x90000
	v_lshl_add_u64 v[208:209], v[226:227], 0, s[6:7]
	v_lshl_add_u64 v[132:133], v[134:135], 0, v[208:209]
	global_load_dwordx4 v[152:155], v[132:133], off
	global_load_dwordx4 v[148:151], v[132:133], off offset:256
	s_mov_b64 s[6:7], 0xa0000
	v_lshl_add_u64 v[206:207], v[226:227], 0, s[6:7]
	v_lshl_add_u64 v[132:133], v[134:135], 0, v[206:207]
	global_load_dwordx4 v[144:147], v[132:133], off
	global_load_dwordx4 v[140:143], v[132:133], off offset:256
	s_mov_b64 s[6:7], 0xb0000
	v_lshl_add_u64 v[204:205], v[226:227], 0, s[6:7]
	v_lshl_add_u64 v[132:133], v[134:135], 0, v[204:205]
	global_load_dwordx4 v[136:139], v[132:133], off
	s_nop 0
	global_load_dwordx4 v[132:135], v[132:133], off offset:256
	s_and_b64 vcc, exec, s[42:43]
	s_mov_b32 s45, s0
	s_mov_b32 s46, s14
	s_mov_b64 s[20:21], s[18:19]
	s_mov_b64 s[6:7], s[4:5]
	s_waitcnt vmcnt(15)
; __device__ __forceinline__ unsigned cvt_pk_bf16(float lo, float hi) { const f32x2 v = {lo, hi}; const bf16v2_ r = __builtin_convertvector(v, bf16v2_); return __builtin_bit_cast(unsigned, r); }
; __device__ __forceinline__ float bflo(unsigned w) { return __uint_as_float(w << 16); }
; __device__ __forceinline__ float bfhi(unsigned w) { return __uint_as_float(w & 0xffff0000u); }
;     __device__ __forceinline__ void operator()(const f32x4 (&acc)[2][2][4][2], const Unit& u, int wr, int wc, int, int) const {
;     ...
;                 for (int bj = 0; bj < 2; ++bj) { const u32x4 c = cin[ai][m][bj]; const f32x4 v0 = acc[ai][bj][m][0], v1 = acc[ai][bj][m][1];
;                     u32x4 w; w.x = cvt_pk_bf16(bflo(c.x) + v0[0], bfhi(c.x) + v0[1]); w.y = cvt_pk_bf16(bflo(c.y) + v0[2], bfhi(c.y) + v0[3]);
;                     w.z = cvt_pk_bf16(bflo(c.z) + v1[0], bfhi(c.z) + v1[1]); w.w = cvt_pk_bf16(bflo(c.w) + v1[2], bfhi(c.w) + v1[3]);
;                     *(u32x4*)(C + (size_t)(row0 + ai * HALF + m * 16) * ldc + col0 + bj * HALF) = w; }
	v_lshlrev_b32_e32 v228, 16, v216
	v_and_b32_e32 v229, 0xffff0000, v216
	v_lshlrev_b32_e32 v216, 16, v217
	v_and_b32_e32 v217, 0xffff0000, v217
	v_pk_add_f32 v[128:129], v[128:129], v[228:229]
	v_pk_add_f32 v[130:131], v[130:131], v[216:217]
	v_cvt_pk_bf16_f32 v128, v128, v129
	v_cvt_pk_bf16_f32 v129, v130, v131
	v_lshlrev_b32_e32 v130, 16, v218
	v_and_b32_e32 v131, 0xffff0000, v218
	v_pk_add_f32 v[124:125], v[124:125], v[130:131]
	s_nop 0
	v_cvt_pk_bf16_f32 v130, v124, v125
	v_lshlrev_b32_e32 v124, 16, v219
	v_and_b32_e32 v125, 0xffff0000, v219
	v_pk_add_f32 v[124:125], v[126:127], v[124:125]
	s_waitcnt vmcnt(14)
	v_lshlrev_b32_e32 v126, 16, v188
	v_and_b32_e32 v127, 0xffff0000, v188
	v_pk_add_f32 v[120:121], v[120:121], v[126:127]
	v_lshlrev_b32_e32 v126, 16, v189
	v_and_b32_e32 v127, 0xffff0000, v189
	v_pk_add_f32 v[122:123], v[122:123], v[126:127]
	v_cvt_pk_bf16_f32 v120, v120, v121
	v_cvt_pk_bf16_f32 v121, v122, v123
	v_lshlrev_b32_e32 v122, 16, v190
	v_and_b32_e32 v123, 0xffff0000, v190
	v_pk_add_f32 v[116:117], v[116:117], v[122:123]
	v_cvt_pk_bf16_f32 v131, v124, v125
	v_cvt_pk_bf16_f32 v122, v116, v117
	v_lshlrev_b32_e32 v116, 16, v191
	v_and_b32_e32 v117, 0xffff0000, v191
	v_pk_add_f32 v[116:117], v[118:119], v[116:117]
	v_lshl_add_u64 v[124:125], s[88:89], 0, v[226:227]
	v_cvt_pk_bf16_f32 v123, v116, v117
	s_waitcnt vmcnt(13)
	v_lshlrev_b32_e32 v116, 16, v184
	v_and_b32_e32 v117, 0xffff0000, v184
	v_pk_add_f32 v[112:113], v[112:113], v[116:117]
	v_lshlrev_b32_e32 v116, 16, v185
	v_and_b32_e32 v117, 0xffff0000, v185
	v_pk_add_f32 v[114:115], v[114:115], v[116:117]
	v_cvt_pk_bf16_f32 v112, v112, v113
	v_cvt_pk_bf16_f32 v113, v114, v115
	v_lshlrev_b32_e32 v114, 16, v186
	v_and_b32_e32 v115, 0xffff0000, v186
	v_pk_add_f32 v[108:109], v[108:109], v[114:115]
	v_lshl_add_u64 v[124:125], v[124:125], 0, v[202:203]
	v_cvt_pk_bf16_f32 v114, v108, v109
	v_lshlrev_b32_e32 v108, 16, v187
	v_and_b32_e32 v109, 0xffff0000, v187
	v_pk_add_f32 v[108:109], v[110:111], v[108:109]
	s_waitcnt vmcnt(12)
	v_lshlrev_b32_e32 v110, 16, v180
	v_and_b32_e32 v111, 0xffff0000, v180
	v_pk_add_f32 v[104:105], v[104:105], v[110:111]
	v_lshlrev_b32_e32 v110, 16, v181
	v_and_b32_e32 v111, 0xffff0000, v181
	v_pk_add_f32 v[106:107], v[106:107], v[110:111]
	v_cvt_pk_bf16_f32 v104, v104, v105
	v_cvt_pk_bf16_f32 v105, v106, v107
	v_lshlrev_b32_e32 v106, 16, v182
	v_and_b32_e32 v107, 0xffff0000, v182
	v_pk_add_f32 v[96:97], v[96:97], v[106:107]
	v_cvt_pk_bf16_f32 v115, v108, v109
	v_cvt_pk_bf16_f32 v106, v96, v97
	v_lshlrev_b32_e32 v96, 16, v183
	v_and_b32_e32 v97, 0xffff0000, v183
	v_pk_add_f32 v[96:97], v[98:99], v[96:97]
	s_waitcnt vmcnt(11)
	v_lshlrev_b32_e32 v98, 16, v177
	v_cvt_pk_bf16_f32 v107, v96, v97
	v_lshlrev_b32_e32 v96, 16, v176
	v_and_b32_e32 v97, 0xffff0000, v176
	v_and_b32_e32 v99, 0xffff0000, v177
	v_pk_add_f32 v[96:97], v[100:101], v[96:97]
	v_pk_add_f32 v[98:99], v[102:103], v[98:99]
	v_cvt_pk_bf16_f32 v96, v96, v97
	v_cvt_pk_bf16_f32 v97, v98, v99
	v_lshlrev_b32_e32 v98, 16, v178
	v_and_b32_e32 v99, 0xffff0000, v178
	v_pk_add_f32 v[92:93], v[92:93], v[98:99]
	v_lshl_add_u64 v[108:109], s[88:89], 0, v[222:223]
	v_cvt_pk_bf16_f32 v98, v92, v93
	v_lshlrev_b32_e32 v92, 16, v179
	v_and_b32_e32 v93, 0xffff0000, v179
	v_pk_add_f32 v[92:93], v[94:95], v[92:93]
	s_waitcnt vmcnt(10)
	v_lshlrev_b32_e32 v94, 16, v168
	v_and_b32_e32 v95, 0xffff0000, v168
	v_pk_add_f32 v[88:89], v[88:89], v[94:95]
	v_lshlrev_b32_e32 v94, 16, v169
	v_and_b32_e32 v95, 0xffff0000, v169
	v_pk_add_f32 v[90:91], v[90:91], v[94:95]
	v_cvt_pk_bf16_f32 v88, v88, v89
	v_cvt_pk_bf16_f32 v89, v90, v91
	v_lshlrev_b32_e32 v90, 16, v170
	v_and_b32_e32 v91, 0xffff0000, v170
	v_pk_add_f32 v[80:81], v[80:81], v[90:91]
	v_cvt_pk_bf16_f32 v99, v92, v93
	v_cvt_pk_bf16_f32 v90, v80, v81
	v_lshlrev_b32_e32 v80, 16, v171
	v_and_b32_e32 v81, 0xffff0000, v171
	v_pk_add_f32 v[80:81], v[82:83], v[80:81]
	s_waitcnt vmcnt(9)
	v_lshlrev_b32_e32 v82, 16, v173
	v_cvt_pk_bf16_f32 v91, v80, v81
	v_lshlrev_b32_e32 v80, 16, v172
	v_and_b32_e32 v81, 0xffff0000, v172
	v_and_b32_e32 v83, 0xffff0000, v173
	v_pk_add_f32 v[80:81], v[84:85], v[80:81]
	v_pk_add_f32 v[82:83], v[86:87], v[82:83]
	v_cvt_pk_bf16_f32 v80, v80, v81
	v_cvt_pk_bf16_f32 v81, v82, v83
	v_lshlrev_b32_e32 v82, 16, v174
	v_and_b32_e32 v83, 0xffff0000, v174
	v_pk_add_f32 v[76:77], v[76:77], v[82:83]
	v_lshl_add_u64 v[92:93], s[88:89], 0, v[220:221]
	v_cvt_pk_bf16_f32 v82, v76, v77
	v_lshlrev_b32_e32 v76, 16, v175
	v_and_b32_e32 v77, 0xffff0000, v175
	v_pk_add_f32 v[76:77], v[78:79], v[76:77]
	s_waitcnt vmcnt(8)
	v_lshlrev_b32_e32 v78, 16, v164
	v_and_b32_e32 v79, 0xffff0000, v164
	v_pk_add_f32 v[72:73], v[72:73], v[78:79]
	v_lshlrev_b32_e32 v78, 16, v165
	v_and_b32_e32 v79, 0xffff0000, v165
	v_pk_add_f32 v[74:75], v[74:75], v[78:79]
	v_cvt_pk_bf16_f32 v72, v72, v73
	v_cvt_pk_bf16_f32 v73, v74, v75
	v_lshlrev_b32_e32 v74, 16, v166
	v_and_b32_e32 v75, 0xffff0000, v166
	v_pk_add_f32 v[68:69], v[68:69], v[74:75]
	v_cvt_pk_bf16_f32 v83, v76, v77
	v_cvt_pk_bf16_f32 v74, v68, v69
	v_lshlrev_b32_e32 v68, 16, v167
	v_and_b32_e32 v69, 0xffff0000, v167
	v_pk_add_f32 v[68:69], v[70:71], v[68:69]
	v_lshl_add_u64 v[76:77], s[88:89], 0, v[212:213]
	v_cvt_pk_bf16_f32 v75, v68, v69
	s_waitcnt vmcnt(7)
	v_lshlrev_b32_e32 v68, 16, v160
	v_and_b32_e32 v69, 0xffff0000, v160
	v_pk_add_f32 v[64:65], v[64:65], v[68:69]
	v_lshlrev_b32_e32 v68, 16, v161
	v_and_b32_e32 v69, 0xffff0000, v161
	v_pk_add_f32 v[66:67], v[66:67], v[68:69]
	v_cvt_pk_bf16_f32 v64, v64, v65
	v_cvt_pk_bf16_f32 v65, v66, v67
	v_lshlrev_b32_e32 v66, 16, v162
	v_and_b32_e32 v67, 0xffff0000, v162
	v_pk_add_f32 v[60:61], v[60:61], v[66:67]
	v_lshl_add_u64 v[108:109], v[108:109], 0, v[202:203]
	v_cvt_pk_bf16_f32 v66, v60, v61
	v_lshlrev_b32_e32 v60, 16, v163
	v_and_b32_e32 v61, 0xffff0000, v163
	v_pk_add_f32 v[60:61], v[62:63], v[60:61]
	s_waitcnt vmcnt(6)
; __device__ __forceinline__ unsigned cvt_pk_bf16(float lo, float hi) { const f32x2 v = {lo, hi}; const bf16v2_ r = __builtin_convertvector(v, bf16v2_); return __builtin_bit_cast(unsigned, r); }
; __device__ __forceinline__ float bflo(unsigned w) { return __uint_as_float(w << 16); }
; __device__ __forceinline__ float bfhi(unsigned w) { return __uint_as_float(w & 0xffff0000u); }
;     __device__ __forceinline__ void operator()(const f32x4 (&acc)[2][2][4][2], const Unit& u, int wr, int wc, int, int) const {
;     ...
;                 for (int bj = 0; bj < 2; ++bj) { const u32x4 c = cin[ai][m][bj]; const f32x4 v0 = acc[ai][bj][m][0], v1 = acc[ai][bj][m][1];
;                     u32x4 w; w.x = cvt_pk_bf16(bflo(c.x) + v0[0], bfhi(c.x) + v0[1]); w.y = cvt_pk_bf16(bflo(c.y) + v0[2], bfhi(c.y) + v0[3]);
;                     w.z = cvt_pk_bf16(bflo(c.z) + v1[0], bfhi(c.z) + v1[1]); w.w = cvt_pk_bf16(bflo(c.w) + v1[2], bfhi(c.w) + v1[3]);
;                     *(u32x4*)(C + (size_t)(row0 + ai * HALF + m * 16) * ldc + col0 + bj * HALF) = w; }
	v_lshlrev_b32_e32 v62, 16, v156
	v_and_b32_e32 v63, 0xffff0000, v156
	v_pk_add_f32 v[56:57], v[56:57], v[62:63]
	v_lshlrev_b32_e32 v62, 16, v157
	v_and_b32_e32 v63, 0xffff0000, v157
	v_pk_add_f32 v[58:59], v[58:59], v[62:63]
	v_cvt_pk_bf16_f32 v56, v56, v57
	v_cvt_pk_bf16_f32 v57, v58, v59
	v_lshlrev_b32_e32 v58, 16, v158
	v_and_b32_e32 v59, 0xffff0000, v158
	v_pk_add_f32 v[48:49], v[48:49], v[58:59]
	v_cvt_pk_bf16_f32 v67, v60, v61
	v_cvt_pk_bf16_f32 v58, v48, v49
	v_lshlrev_b32_e32 v48, 16, v159
	v_and_b32_e32 v49, 0xffff0000, v159
	v_pk_add_f32 v[48:49], v[50:51], v[48:49]
	s_waitcnt vmcnt(5)
	v_lshlrev_b32_e32 v50, 16, v153
	v_cvt_pk_bf16_f32 v59, v48, v49
	v_lshlrev_b32_e32 v48, 16, v152
	v_and_b32_e32 v49, 0xffff0000, v152
	v_and_b32_e32 v51, 0xffff0000, v153
	v_pk_add_f32 v[48:49], v[52:53], v[48:49]
	v_pk_add_f32 v[50:51], v[54:55], v[50:51]
	v_cvt_pk_bf16_f32 v48, v48, v49
	v_cvt_pk_bf16_f32 v49, v50, v51
	v_lshlrev_b32_e32 v50, 16, v154
	v_and_b32_e32 v51, 0xffff0000, v154
	v_pk_add_f32 v[44:45], v[44:45], v[50:51]
	v_lshl_add_u64 v[60:61], s[88:89], 0, v[210:211]
	v_cvt_pk_bf16_f32 v50, v44, v45
	v_lshlrev_b32_e32 v44, 16, v155
	v_and_b32_e32 v45, 0xffff0000, v155
	v_pk_add_f32 v[44:45], v[46:47], v[44:45]
	s_waitcnt vmcnt(4)
	v_lshlrev_b32_e32 v46, 16, v148
	v_and_b32_e32 v47, 0xffff0000, v148
	v_pk_add_f32 v[40:41], v[40:41], v[46:47]
	v_lshlrev_b32_e32 v46, 16, v149
	v_and_b32_e32 v47, 0xffff0000, v149
	v_pk_add_f32 v[42:43], v[42:43], v[46:47]
	v_cvt_pk_bf16_f32 v40, v40, v41
	v_cvt_pk_bf16_f32 v41, v42, v43
	v_lshlrev_b32_e32 v42, 16, v150
	v_and_b32_e32 v43, 0xffff0000, v150
	v_pk_add_f32 v[32:33], v[32:33], v[42:43]
	v_cvt_pk_bf16_f32 v51, v44, v45
	v_cvt_pk_bf16_f32 v42, v32, v33
	v_lshlrev_b32_e32 v32, 16, v151
	v_and_b32_e32 v33, 0xffff0000, v151
	v_pk_add_f32 v[32:33], v[34:35], v[32:33]
	s_waitcnt vmcnt(3)
	v_lshlrev_b32_e32 v34, 16, v145
	v_cvt_pk_bf16_f32 v43, v32, v33
	v_lshlrev_b32_e32 v32, 16, v144
	v_and_b32_e32 v33, 0xffff0000, v144
	v_and_b32_e32 v35, 0xffff0000, v145
	v_pk_add_f32 v[32:33], v[36:37], v[32:33]
	v_pk_add_f32 v[34:35], v[38:39], v[34:35]
	v_cvt_pk_bf16_f32 v32, v32, v33
	v_cvt_pk_bf16_f32 v33, v34, v35
	v_lshlrev_b32_e32 v34, 16, v146
	v_and_b32_e32 v35, 0xffff0000, v146
	v_pk_add_f32 v[28:29], v[28:29], v[34:35]
	v_lshl_add_u64 v[44:45], s[88:89], 0, v[208:209]
	v_cvt_pk_bf16_f32 v34, v28, v29
	v_lshlrev_b32_e32 v28, 16, v147
	v_and_b32_e32 v29, 0xffff0000, v147
	v_pk_add_f32 v[28:29], v[30:31], v[28:29]
	s_waitcnt vmcnt(2)
	v_lshlrev_b32_e32 v30, 16, v140
	v_and_b32_e32 v31, 0xffff0000, v140
	v_pk_add_f32 v[24:25], v[24:25], v[30:31]
	v_lshlrev_b32_e32 v30, 16, v141
	v_and_b32_e32 v31, 0xffff0000, v141
	v_pk_add_f32 v[26:27], v[26:27], v[30:31]
	v_cvt_pk_bf16_f32 v24, v24, v25
	v_cvt_pk_bf16_f32 v25, v26, v27
	v_lshlrev_b32_e32 v26, 16, v142
	v_and_b32_e32 v27, 0xffff0000, v142
	v_pk_add_f32 v[16:17], v[16:17], v[26:27]
	v_cvt_pk_bf16_f32 v35, v28, v29
	v_cvt_pk_bf16_f32 v26, v16, v17
	v_lshlrev_b32_e32 v16, 16, v143
	v_and_b32_e32 v17, 0xffff0000, v143
	v_pk_add_f32 v[16:17], v[18:19], v[16:17]
	s_waitcnt vmcnt(1)
	v_lshlrev_b32_e32 v18, 16, v137
	v_cvt_pk_bf16_f32 v27, v16, v17
	v_lshlrev_b32_e32 v16, 16, v136
	v_and_b32_e32 v17, 0xffff0000, v136
	v_and_b32_e32 v19, 0xffff0000, v137
	v_pk_add_f32 v[16:17], v[20:21], v[16:17]
	v_pk_add_f32 v[18:19], v[22:23], v[18:19]
	v_cvt_pk_bf16_f32 v16, v16, v17
	v_cvt_pk_bf16_f32 v17, v18, v19
	v_lshlrev_b32_e32 v18, 16, v138
	v_and_b32_e32 v19, 0xffff0000, v138
	v_pk_add_f32 v[12:13], v[12:13], v[18:19]
	v_lshl_add_u64 v[28:29], s[88:89], 0, v[206:207]
	v_cvt_pk_bf16_f32 v18, v12, v13
	v_lshlrev_b32_e32 v12, 16, v139
	v_and_b32_e32 v13, 0xffff0000, v139
	v_pk_add_f32 v[12:13], v[14:15], v[12:13]
	s_waitcnt vmcnt(0)
; __device__ __forceinline__ unsigned cvt_pk_bf16(float lo, float hi) { const f32x2 v = {lo, hi}; const bf16v2_ r = __builtin_convertvector(v, bf16v2_); return __builtin_bit_cast(unsigned, r); }
; __device__ __forceinline__ float bflo(unsigned w) { return __uint_as_float(w << 16); }
; __device__ __forceinline__ float bfhi(unsigned w) { return __uint_as_float(w & 0xffff0000u); }
;     __device__ __forceinline__ void operator()(const f32x4 (&acc)[2][2][4][2], const Unit& u, int wr, int wc, int, int) const {
;     ...
;                 for (int bj = 0; bj < 2; ++bj) cin[ai][m][bj] = *(const u32x4*)(C + (size_t)(row0 + ai * HALF + m * 16) * ldc + col0 + bj * HALF);
; #pragma unroll
;         for (int ai = 0; ai < 2; ++ai)
; #pragma unroll
;             for (int m = 0; m < 4; ++m)
; #pragma unroll
;                 for (int bj = 0; bj < 2; ++bj) { const u32x4 c = cin[ai][m][bj]; const f32x4 v0 = acc[ai][bj][m][0], v1 = acc[ai][bj][m][1];
;                     u32x4 w; w.x = cvt_pk_bf16(bflo(c.x) + v0[0], bfhi(c.x) + v0[1]); w.y = cvt_pk_bf16(bflo(c.y) + v0[2], bfhi(c.y) + v0[3]);
;                     w.z = cvt_pk_bf16(bflo(c.z) + v1[0], bfhi(c.z) + v1[1]); w.w = cvt_pk_bf16(bflo(c.w) + v1[2], bfhi(c.w) + v1[3]);
;                     *(u32x4*)(C + (size_t)(row0 + ai * HALF + m * 16) * ldc + col0 + bj * HALF) = w; }
	v_lshlrev_b32_e32 v14, 16, v132
	v_and_b32_e32 v15, 0xffff0000, v132
	v_pk_add_f32 v[8:9], v[8:9], v[14:15]
	v_lshlrev_b32_e32 v14, 16, v133
	v_and_b32_e32 v15, 0xffff0000, v133
	v_pk_add_f32 v[10:11], v[10:11], v[14:15]
	v_cvt_pk_bf16_f32 v8, v8, v9
	v_cvt_pk_bf16_f32 v9, v10, v11
	v_lshlrev_b32_e32 v10, 16, v134
	v_and_b32_e32 v11, 0xffff0000, v134
	v_pk_add_f32 v[4:5], v[4:5], v[10:11]
	v_cvt_pk_bf16_f32 v19, v12, v13
	v_cvt_pk_bf16_f32 v10, v4, v5
	v_lshlrev_b32_e32 v4, 16, v135
	v_and_b32_e32 v5, 0xffff0000, v135
	v_lshl_add_u64 v[12:13], s[88:89], 0, v[204:205]
	v_pk_add_f32 v[4:5], v[6:7], v[4:5]
	v_lshl_add_u64 v[92:93], v[92:93], 0, v[202:203]
	v_lshl_add_u64 v[76:77], v[76:77], 0, v[202:203]
	v_lshl_add_u64 v[60:61], v[60:61], 0, v[202:203]
	v_lshl_add_u64 v[44:45], v[44:45], 0, v[202:203]
	v_lshl_add_u64 v[28:29], v[28:29], 0, v[202:203]
	v_lshl_add_u64 v[12:13], v[12:13], 0, v[202:203]
	v_cvt_pk_bf16_f32 v11, v4, v5
	global_store_dwordx4 v[124:125], v[128:131], off
	global_store_dwordx4 v[124:125], v[120:123], off offset:256
	global_store_dwordx4 v[108:109], v[112:115], off
	global_store_dwordx4 v[108:109], v[104:107], off offset:256
	global_store_dwordx4 v[92:93], v[96:99], off
	global_store_dwordx4 v[92:93], v[88:91], off offset:256
	global_store_dwordx4 v[76:77], v[80:83], off
	global_store_dwordx4 v[76:77], v[72:75], off offset:256
	global_store_dwordx4 v[60:61], v[64:67], off
	global_store_dwordx4 v[60:61], v[56:59], off offset:256
	global_store_dwordx4 v[44:45], v[48:51], off
	global_store_dwordx4 v[44:45], v[40:43], off offset:256
	global_store_dwordx4 v[28:29], v[32:35], off
	global_store_dwordx4 v[28:29], v[24:27], off offset:256
	global_store_dwordx4 v[12:13], v[16:19], off
	global_store_dwordx4 v[12:13], v[8:11], off offset:256
	v_subrev_u32_e32 v216, s88, v124
	v_bfe_u32 v217, v216, 4, 8
	v_lshrrev_b32_e32 v216, 12, v216
	v_and_b32_e32 v218, 15, v217
	v_lshrrev_b32_e32 v217, 5, v217
	v_lshl_or_b32 v217, v217, 4, v218
	v_lshlrev_b32_e32 v217, 17, v217
	v_lshl_add_u32 v216, v216, 2, v217
	v_add_u32_e32 v216, 0x1e000000, v216
	v_mov_b32_e32 v188, 0
	v_dot2c_f32_bf16_e32 v188, v128, v128
	v_dot2c_f32_bf16_e32 v188, v129, v129
	v_dot2c_f32_bf16_e32 v188, v130, v130
	v_dot2c_f32_bf16_e32 v188, v131, v131
	v_dot2c_f32_bf16_e32 v188, v120, v120
	v_dot2c_f32_bf16_e32 v188, v121, v121
	v_dot2c_f32_bf16_e32 v188, v122, v122
	v_dot2c_f32_bf16_e32 v188, v123, v123
	s_nop 2
	global_store_dword v216, v188, s[88:89]
	v_mov_b32_e32 v189, 0
	v_dot2c_f32_bf16_e32 v189, v112, v112
	v_dot2c_f32_bf16_e32 v189, v113, v113
	v_dot2c_f32_bf16_e32 v189, v114, v114
	v_dot2c_f32_bf16_e32 v189, v115, v115
	v_dot2c_f32_bf16_e32 v189, v104, v104
	v_dot2c_f32_bf16_e32 v189, v105, v105
	v_dot2c_f32_bf16_e32 v189, v106, v106
	v_dot2c_f32_bf16_e32 v189, v107, v107
	s_nop 2
	global_store_dword v216, v189, s[88:89] offset:64
	v_mov_b32_e32 v188, 0
	v_dot2c_f32_bf16_e32 v188, v96, v96
	v_dot2c_f32_bf16_e32 v188, v97, v97
	v_dot2c_f32_bf16_e32 v188, v98, v98
	v_dot2c_f32_bf16_e32 v188, v99, v99
	v_dot2c_f32_bf16_e32 v188, v88, v88
	v_dot2c_f32_bf16_e32 v188, v89, v89
	v_dot2c_f32_bf16_e32 v188, v90, v90
	v_dot2c_f32_bf16_e32 v188, v91, v91
	s_nop 2
	global_store_dword v216, v188, s[88:89] offset:128
	v_mov_b32_e32 v189, 0
	v_dot2c_f32_bf16_e32 v189, v80, v80
	v_dot2c_f32_bf16_e32 v189, v81, v81
	v_dot2c_f32_bf16_e32 v189, v82, v82
	v_dot2c_f32_bf16_e32 v189, v83, v83
	v_dot2c_f32_bf16_e32 v189, v72, v72
	v_dot2c_f32_bf16_e32 v189, v73, v73
	v_dot2c_f32_bf16_e32 v189, v74, v74
	v_dot2c_f32_bf16_e32 v189, v75, v75
	s_nop 2
	global_store_dword v216, v189, s[88:89] offset:192
	v_mov_b32_e32 v188, 0
	v_dot2c_f32_bf16_e32 v188, v64, v64
	v_dot2c_f32_bf16_e32 v188, v65, v65
	v_dot2c_f32_bf16_e32 v188, v66, v66
	v_dot2c_f32_bf16_e32 v188, v67, v67
	v_dot2c_f32_bf16_e32 v188, v56, v56
	v_dot2c_f32_bf16_e32 v188, v57, v57
	v_dot2c_f32_bf16_e32 v188, v58, v58
	v_dot2c_f32_bf16_e32 v188, v59, v59
	s_nop 2
	global_store_dword v216, v188, s[88:89] offset:512
	v_mov_b32_e32 v189, 0
	v_dot2c_f32_bf16_e32 v189, v48, v48
	v_dot2c_f32_bf16_e32 v189, v49, v49
	v_dot2c_f32_bf16_e32 v189, v50, v50
	v_dot2c_f32_bf16_e32 v189, v51, v51
	v_dot2c_f32_bf16_e32 v189, v40, v40
	v_dot2c_f32_bf16_e32 v189, v41, v41
	v_dot2c_f32_bf16_e32 v189, v42, v42
	v_dot2c_f32_bf16_e32 v189, v43, v43
	s_nop 2
	global_store_dword v216, v189, s[88:89] offset:576
	v_mov_b32_e32 v188, 0
	v_dot2c_f32_bf16_e32 v188, v32, v32
	v_dot2c_f32_bf16_e32 v188, v33, v33
	v_dot2c_f32_bf16_e32 v188, v34, v34
	v_dot2c_f32_bf16_e32 v188, v35, v35
	v_dot2c_f32_bf16_e32 v188, v24, v24
	v_dot2c_f32_bf16_e32 v188, v25, v25
	v_dot2c_f32_bf16_e32 v188, v26, v26
	v_dot2c_f32_bf16_e32 v188, v27, v27
	s_nop 2
	global_store_dword v216, v188, s[88:89] offset:640
	v_mov_b32_e32 v189, 0
	v_dot2c_f32_bf16_e32 v189, v16, v16
	v_dot2c_f32_bf16_e32 v189, v17, v17
	v_dot2c_f32_bf16_e32 v189, v18, v18
	v_dot2c_f32_bf16_e32 v189, v19, v19
	v_dot2c_f32_bf16_e32 v189, v8, v8
	v_dot2c_f32_bf16_e32 v189, v9, v9
	v_dot2c_f32_bf16_e32 v189, v10, v10
	v_dot2c_f32_bf16_e32 v189, v11, v11
	s_nop 2
	global_store_dword v216, v189, s[88:89] offset:704
	s_cbranch_vccz .LBB0_959
	s_waitcnt vmcnt(0)
	s_cmpk_gt_u32 s2, 0xff
	s_cbranch_scc1 .LBB0_970
	s_barrier

; #define PG8_STAGE(bufoff, gbase, voff) do { _Pragma("unroll") for (int _i = 0; _i < 2; ++_i) \
;         __builtin_amdgcn_global_load_lds((const unsigned*)((const char*)(gbase) + (voff)[_i]), (LAS unsigned*)(lds + (bufoff) + ldsw + _i * 8192), 16, 0, 0); } while (0)
; #define PG8_LDA(dst, b, h) do { _Pragma("unroll") for (int m = 0; m < 4; ++m) _Pragma("unroll") for (int k = 0; k < 2; ++k) dst[m][k] = *(const LAS bf16x8*)(lds + PG8_SA(b, h) + aoff + m * 2048 + k * 1024); } while (0)
; #define PG8_LDB(dst, b, h) do { _Pragma("unroll") for (int n = 0; n < 2; ++n) _Pragma("unroll") for (int k = 0; k < 2; ++k) dst[n][k] = *(const LAS bf16x8*)(lds + PG8_SB(b, h) + boff + n * 2048 + k * 1024); } while (0)
; #define PG8_MMA(ai, bj, At, Bt) do { __builtin_amdgcn_s_setprio(1); _Pragma("unroll") for (int m = 0; m < 4; ++m) _Pragma("unroll") for (int n = 0; n < 2; ++n) _Pragma("unroll") for (int k = 0; k < 2; ++k) \
;         acc[ai][bj][m][n] = __builtin_amdgcn_mfma_f32_16x16x32_bf16(Bt[n][k], At[m][k], acc[ai][bj][m][n], 0, 0, 0); __builtin_amdgcn_s_setprio(0); } while (0)
; #define PG8_WAIT_V(n) asm volatile("s_waitcnt vmcnt(" #n ")" ::: "memory")
; #define PG8_WAIT_L(n) asm volatile("s_waitcnt lgkmcnt(" #n ")" ::: "memory")
; #define PG8_BAR __builtin_amdgcn_s_barrier()
; #define PG8_SCHED __builtin_amdgcn_sched_barrier(0)
; template <class Epi, class Sched>
; __device__ __forceinline__ void gemm_phase(LAS unsigned char* lds, const Gemm g, const Sched& S, const Epi& E) {
;     ...
;             PG8_LDB(B0, 0, 0); PG8_SCHED; PG8_LDA(At, 0, 0); PG8_STAGE(PG8_SA(1, 1), a1 + hstepA, voffA);
;             PG8_WAIT_L(8); PG8_BAR; PG8_WAIT_L(0); PG8_MMA(0, 0, At, B0); PG8_BAR; PG8_SCHED;
;             PG8_LDB(B1, 0, 1); PG8_STAGE(PG8_SB(0, 0), b2, voffB);
;             PG8_BAR; PG8_WAIT_L(0); PG8_MMA(0, 1, At, B1); PG8_BAR;
;             PG8_LDA(At, 0, 1); PG8_STAGE(PG8_SA(0, 0), a2, voffA);
;             PG8_BAR; PG8_WAIT_L(0); PG8_MMA(1, 0, At, B0); PG8_BAR; PG8_SCHED;
;             PG8_STAGE(PG8_SB(0, 1), b2 + hstepB, voffB);
;             PG8_WAIT_V(6); PG8_BAR; PG8_MMA(1, 1, At, B1); PG8_BAR;
.LBB0_1396:
	s_setprio 0
	s_add_u32 s20, s6, 0xfff80080
	s_addc_u32 s21, s7, -1
	s_add_i32 s52, 0, 0x10000
	v_add_u32_e32 v144, s52, v1
	ds_read_b128 v[132:135], v144
	ds_read_b128 v[136:139], v144 offset:1024
	ds_read_b128 v[140:143], v144 offset:2048
	ds_read_b128 v[144:147], v144 offset:3072
	s_cmp_eq_u32 s51, 28
	s_cselect_b32 s25, s15, s21
	s_cselect_b32 s24, s47, s20
	s_cselect_b32 s21, s1, s50
	s_cselect_b32 s20, s48, s49
	ds_read_b128 v[148:151], v224
	ds_read_b128 v[152:155], v224 offset:1024
	ds_read_b128 v[156:159], v224 offset:2048
	ds_read_b128 v[160:163], v224 offset:3072
	ds_read_b128 v[164:167], v224 offset:4096
	ds_read_b128 v[168:171], v224 offset:5120
	ds_read_b128 v[172:175], v224 offset:6144
	ds_read_b128 v[176:179], v224 offset:7168
	s_add_i32 s54, 0, 0x14000
	v_add_u32_e32 v202, s54, v1
	ds_read_b128 v[180:183], v202
	ds_read_b128 v[184:187], v202 offset:1024
	ds_read_b128 v[188:191], v202 offset:2048
	ds_read_b128 v[202:205], v202 offset:3072
	s_add_i32 m0, s31, 0xc000
	s_nop 0
	global_load_lds_dwordx4 v198, s[6:7]
	s_add_i32 m0, s31, 0xe000
	s_nop 0
	global_load_lds_dwordx4 v200, s[6:7]
	s_waitcnt lgkmcnt(0)
	s_setprio 1
	s_barrier
	v_mfma_f32_16x16x32_bf16 v[128:131], v[132:135], v[148:151], v[128:131]
	v_mfma_f32_16x16x32_bf16 v[124:127], v[140:143], v[148:151], v[124:127]
	v_mfma_f32_16x16x32_bf16 v[112:115], v[132:135], v[156:159], v[112:115]
	v_mfma_f32_16x16x32_bf16 v[108:111], v[140:143], v[156:159], v[108:111]
	v_mfma_f32_16x16x32_bf16 v[100:103], v[132:135], v[164:167], v[100:103]
	v_mfma_f32_16x16x32_bf16 v[92:95], v[140:143], v[164:167], v[92:95]
	v_mfma_f32_16x16x32_bf16 v[84:87], v[132:135], v[172:175], v[84:87]
	v_mfma_f32_16x16x32_bf16 v[76:79], v[140:143], v[172:175], v[76:79]
	v_mfma_f32_16x16x32_bf16 v[128:131], v[136:139], v[152:155], v[128:131]
	v_mfma_f32_16x16x32_bf16 v[124:127], v[144:147], v[152:155], v[124:127]
	v_mfma_f32_16x16x32_bf16 v[112:115], v[136:139], v[160:163], v[112:115]
	v_mfma_f32_16x16x32_bf16 v[108:111], v[144:147], v[160:163], v[108:111]
	v_mfma_f32_16x16x32_bf16 v[100:103], v[136:139], v[168:171], v[100:103]
	v_mfma_f32_16x16x32_bf16 v[92:95], v[144:147], v[168:171], v[92:95]
	v_mfma_f32_16x16x32_bf16 v[84:87], v[136:139], v[176:179], v[84:87]
	v_mfma_f32_16x16x32_bf16 v[76:79], v[144:147], v[176:179], v[76:79]
	v_mfma_f32_16x16x32_bf16 v[120:123], v[180:183], v[148:151], v[120:123]
	v_mfma_f32_16x16x32_bf16 v[116:119], v[188:191], v[148:151], v[116:119]
	v_mfma_f32_16x16x32_bf16 v[104:107], v[180:183], v[156:159], v[104:107]
	v_mfma_f32_16x16x32_bf16 v[96:99], v[188:191], v[156:159], v[96:99]
	v_mfma_f32_16x16x32_bf16 v[88:91], v[180:183], v[164:167], v[88:91]
	v_mfma_f32_16x16x32_bf16 v[80:83], v[188:191], v[164:167], v[80:83]
	v_mfma_f32_16x16x32_bf16 v[72:75], v[180:183], v[172:175], v[72:75]
	v_mfma_f32_16x16x32_bf16 v[68:71], v[188:191], v[172:175], v[68:71]
	v_mfma_f32_16x16x32_bf16 v[120:123], v[184:187], v[152:155], v[120:123]
	v_mfma_f32_16x16x32_bf16 v[116:119], v[202:205], v[152:155], v[116:119]
	v_mfma_f32_16x16x32_bf16 v[104:107], v[184:187], v[160:163], v[104:107]
	v_mfma_f32_16x16x32_bf16 v[96:99], v[202:205], v[160:163], v[96:99]
	v_mfma_f32_16x16x32_bf16 v[88:91], v[184:187], v[168:171], v[88:91]
	v_mfma_f32_16x16x32_bf16 v[80:83], v[202:205], v[168:171], v[80:83]
	v_mfma_f32_16x16x32_bf16 v[72:75], v[184:187], v[176:179], v[72:75]
	v_mfma_f32_16x16x32_bf16 v[68:71], v[202:205], v[176:179], v[68:71]
	s_barrier
	s_setprio 0
	ds_read_b128 v[148:151], v224 offset:16384
	ds_read_b128 v[152:155], v224 offset:17408
	ds_read_b128 v[156:159], v224 offset:18432
	ds_read_b128 v[160:163], v224 offset:19456
	ds_read_b128 v[164:167], v224 offset:20480
	ds_read_b128 v[168:171], v224 offset:21504
	ds_read_b128 v[172:175], v224 offset:22528
	ds_read_b128 v[176:179], v224 offset:23552
	s_add_i32 s52, s52, s30
	v_lshl_add_u64 v[206:207], s[20:21], 0, v[2:3]
	s_mov_b32 m0, s52
	s_nop 0
	global_load_lds_dwordx4 v[206:207], off
	v_lshl_add_u64 v[208:209], s[20:21], 0, v[192:193]
	s_add_i32 m0, s52, 0x2000
	s_nop 0
	global_load_lds_dwordx4 v[208:209], off
	s_mov_b32 m0, s31
	v_lshl_add_u64 v[210:211], s[24:25], 0, v[196:197]
	global_load_lds_dwordx4 v[210:211], off
	v_lshl_add_u64 v[212:213], s[24:25], 0, v[194:195]
	s_mov_b32 m0, s35
	s_nop 0
	global_load_lds_dwordx4 v[212:213], off
	s_add_u32 s52, s20, 0x80000
	s_addc_u32 s53, s21, 0
	s_add_i32 s54, s54, s30
	s_mov_b32 m0, s54
	s_nop 0
	global_load_lds_dwordx4 v2, s[52:53]
	s_add_i32 m0, s54, 0x2000
	s_nop 0
	global_load_lds_dwordx4 v192, s[52:53]
	s_waitcnt lgkmcnt(0)
	s_waitcnt vmcnt(6)
	s_setprio 1
	s_barrier
; #define PG8_STAGE(bufoff, gbase, voff) do { _Pragma("unroll") for (int _i = 0; _i < 2; ++_i) \
;         __builtin_amdgcn_global_load_lds((const unsigned*)((const char*)(gbase) + (voff)[_i]), (LAS unsigned*)(lds + (bufoff) + ldsw + _i * 8192), 16, 0, 0); } while (0)
; #define PG8_LDA(dst, b, h) do { _Pragma("unroll") for (int m = 0; m < 4; ++m) _Pragma("unroll") for (int k = 0; k < 2; ++k) dst[m][k] = *(const LAS bf16x8*)(lds + PG8_SA(b, h) + aoff + m * 2048 + k * 1024); } while (0)
; #define PG8_LDB(dst, b, h) do { _Pragma("unroll") for (int n = 0; n < 2; ++n) _Pragma("unroll") for (int k = 0; k < 2; ++k) dst[n][k] = *(const LAS bf16x8*)(lds + PG8_SB(b, h) + boff + n * 2048 + k * 1024); } while (0)
; #define PG8_MMA(ai, bj, At, Bt) do { __builtin_amdgcn_s_setprio(1); _Pragma("unroll") for (int m = 0; m < 4; ++m) _Pragma("unroll") for (int n = 0; n < 2; ++n) _Pragma("unroll") for (int k = 0; k < 2; ++k) \
;         acc[ai][bj][m][n] = __builtin_amdgcn_mfma_f32_16x16x32_bf16(Bt[n][k], At[m][k], acc[ai][bj][m][n], 0, 0, 0); __builtin_amdgcn_s_setprio(0); } while (0)
; #define PG8_WAIT_V(n) asm volatile("s_waitcnt vmcnt(" #n ")" ::: "memory")
; #define PG8_WAIT_L(n) asm volatile("s_waitcnt lgkmcnt(" #n ")" ::: "memory")
; #define PG8_BAR __builtin_amdgcn_s_barrier()
; #define PG8_SCHED __builtin_amdgcn_sched_barrier(0)
; template <class Epi, class Sched>
; __device__ __forceinline__ void gemm_phase(LAS unsigned char* lds, const Gemm g, const Sched& S, const Epi& E) {
;     ...
;             PG8_WAIT_V(6); PG8_BAR; PG8_MMA(1, 1, At, B1); PG8_BAR;
;             PG8_LDB(B0, 1, 0); PG8_SCHED; PG8_LDA(At, 1, 0); PG8_STAGE(PG8_SA(0, 1), a2 + hstepA, voffA);
;             PG8_WAIT_L(8); PG8_BAR; PG8_WAIT_L(0); PG8_MMA(0, 0, At, B0); PG8_BAR; PG8_SCHED;
;             PG8_LDB(B1, 1, 1); PG8_STAGE(PG8_SB(1, 0), b3, voffB);
;             PG8_BAR; PG8_WAIT_L(0); PG8_MMA(0, 1, At, B1); PG8_BAR;
;             PG8_LDA(At, 1, 1); PG8_STAGE(PG8_SA(1, 0), a3, voffA);
;             PG8_BAR; PG8_WAIT_L(0); PG8_MMA(1, 0, At, B0); PG8_BAR; PG8_SCHED;
	v_mfma_f32_16x16x32_bf16 v[64:67], v[132:135], v[148:151], v[64:67]
	v_mfma_f32_16x16x32_bf16 v[60:63], v[140:143], v[148:151], v[60:63]
	v_mfma_f32_16x16x32_bf16 v[52:55], v[132:135], v[156:159], v[52:55]
	v_mfma_f32_16x16x32_bf16 v[44:47], v[140:143], v[156:159], v[44:47]
	v_mfma_f32_16x16x32_bf16 v[36:39], v[132:135], v[164:167], v[36:39]
	v_mfma_f32_16x16x32_bf16 v[28:31], v[140:143], v[164:167], v[28:31]
	v_mfma_f32_16x16x32_bf16 v[20:23], v[132:135], v[172:175], v[20:23]
	v_mfma_f32_16x16x32_bf16 v[12:15], v[140:143], v[172:175], v[12:15]
	v_mfma_f32_16x16x32_bf16 v[64:67], v[136:139], v[152:155], v[64:67]
	v_mfma_f32_16x16x32_bf16 v[60:63], v[144:147], v[152:155], v[60:63]
	v_mfma_f32_16x16x32_bf16 v[52:55], v[136:139], v[160:163], v[52:55]
	v_mfma_f32_16x16x32_bf16 v[44:47], v[144:147], v[160:163], v[44:47]
	v_mfma_f32_16x16x32_bf16 v[36:39], v[136:139], v[168:171], v[36:39]
	v_mfma_f32_16x16x32_bf16 v[28:31], v[144:147], v[168:171], v[28:31]
	v_mfma_f32_16x16x32_bf16 v[20:23], v[136:139], v[176:179], v[20:23]
	v_mfma_f32_16x16x32_bf16 v[12:15], v[144:147], v[176:179], v[12:15]
	v_mfma_f32_16x16x32_bf16 v[56:59], v[180:183], v[148:151], v[56:59]
	v_mfma_f32_16x16x32_bf16 v[48:51], v[188:191], v[148:151], v[48:51]
	v_mfma_f32_16x16x32_bf16 v[40:43], v[180:183], v[156:159], v[40:43]
	v_mfma_f32_16x16x32_bf16 v[32:35], v[188:191], v[156:159], v[32:35]
	v_mfma_f32_16x16x32_bf16 v[24:27], v[180:183], v[164:167], v[24:27]
	v_mfma_f32_16x16x32_bf16 v[16:19], v[188:191], v[164:167], v[16:19]
	v_mfma_f32_16x16x32_bf16 v[8:11], v[180:183], v[172:175], v[8:11]
	v_mfma_f32_16x16x32_bf16 v[4:7], v[188:191], v[172:175], v[4:7]
	v_mfma_f32_16x16x32_bf16 v[56:59], v[184:187], v[152:155], v[56:59]
	v_mfma_f32_16x16x32_bf16 v[48:51], v[202:205], v[152:155], v[48:51]
	v_mfma_f32_16x16x32_bf16 v[40:43], v[184:187], v[160:163], v[40:43]
	v_mfma_f32_16x16x32_bf16 v[32:35], v[202:205], v[160:163], v[32:35]
	v_mfma_f32_16x16x32_bf16 v[24:27], v[184:187], v[168:171], v[24:27]
	v_mfma_f32_16x16x32_bf16 v[16:19], v[202:205], v[168:171], v[16:19]
	v_mfma_f32_16x16x32_bf16 v[8:11], v[184:187], v[176:179], v[8:11]
	v_mfma_f32_16x16x32_bf16 v[4:7], v[202:205], v[176:179], v[4:7]
	s_barrier
	s_setprio 0
	s_add_i32 s52, 0, 0x18000
	v_add_u32_e32 v144, s52, v1
	ds_read_b128 v[132:135], v144
	ds_read_b128 v[136:139], v144 offset:1024
	ds_read_b128 v[140:143], v144 offset:2048
	ds_read_b128 v[144:147], v144 offset:3072
	s_add_u32 s24, s24, 0x80000
	s_addc_u32 s25, s25, 0
	ds_read_b128 v[148:151], v224 offset:32768
	ds_read_b128 v[152:155], v224 offset:33792
	ds_read_b128 v[156:159], v224 offset:34816
	ds_read_b128 v[160:163], v224 offset:35840
	ds_read_b128 v[164:167], v224 offset:36864
	ds_read_b128 v[168:171], v224 offset:37888
	ds_read_b128 v[172:175], v224 offset:38912
	ds_read_b128 v[176:179], v224 offset:39936
	s_mov_b32 m0, s36
	s_nop 0
	global_load_lds_dwordx4 v196, s[24:25]
	s_mov_b32 m0, s37
	s_nop 0
	global_load_lds_dwordx4 v194, s[24:25]
	s_add_i32 s24, 0, 0x1c000
	v_add_u32_e32 v202, s24, v1
	ds_read_b128 v[180:183], v202
	ds_read_b128 v[184:187], v202 offset:1024
	ds_read_b128 v[188:191], v202 offset:2048
	ds_read_b128 v[202:205], v202 offset:3072
	s_waitcnt lgkmcnt(0)
	s_setprio 1
	s_barrier
	v_mfma_f32_16x16x32_bf16 v[128:131], v[132:135], v[148:151], v[128:131]
	v_mfma_f32_16x16x32_bf16 v[124:127], v[140:143], v[148:151], v[124:127]
	v_mfma_f32_16x16x32_bf16 v[112:115], v[132:135], v[156:159], v[112:115]
	v_mfma_f32_16x16x32_bf16 v[108:111], v[140:143], v[156:159], v[108:111]
	v_mfma_f32_16x16x32_bf16 v[100:103], v[132:135], v[164:167], v[100:103]
	v_mfma_f32_16x16x32_bf16 v[92:95], v[140:143], v[164:167], v[92:95]
	v_mfma_f32_16x16x32_bf16 v[84:87], v[132:135], v[172:175], v[84:87]
	v_mfma_f32_16x16x32_bf16 v[76:79], v[140:143], v[172:175], v[76:79]
	v_mfma_f32_16x16x32_bf16 v[128:131], v[136:139], v[152:155], v[128:131]
	v_mfma_f32_16x16x32_bf16 v[124:127], v[144:147], v[152:155], v[124:127]
	v_mfma_f32_16x16x32_bf16 v[112:115], v[136:139], v[160:163], v[112:115]
	v_mfma_f32_16x16x32_bf16 v[108:111], v[144:147], v[160:163], v[108:111]
	v_mfma_f32_16x16x32_bf16 v[100:103], v[136:139], v[168:171], v[100:103]
	v_mfma_f32_16x16x32_bf16 v[92:95], v[144:147], v[168:171], v[92:95]
	v_mfma_f32_16x16x32_bf16 v[84:87], v[136:139], v[176:179], v[84:87]
	v_mfma_f32_16x16x32_bf16 v[76:79], v[144:147], v[176:179], v[76:79]
	v_mfma_f32_16x16x32_bf16 v[120:123], v[180:183], v[148:151], v[120:123]
	v_mfma_f32_16x16x32_bf16 v[116:119], v[188:191], v[148:151], v[116:119]
	v_mfma_f32_16x16x32_bf16 v[104:107], v[180:183], v[156:159], v[104:107]
	v_mfma_f32_16x16x32_bf16 v[96:99], v[188:191], v[156:159], v[96:99]
	v_mfma_f32_16x16x32_bf16 v[88:91], v[180:183], v[164:167], v[88:91]
	v_mfma_f32_16x16x32_bf16 v[80:83], v[188:191], v[164:167], v[80:83]
	v_mfma_f32_16x16x32_bf16 v[72:75], v[180:183], v[172:175], v[72:75]
	v_mfma_f32_16x16x32_bf16 v[68:71], v[188:191], v[172:175], v[68:71]
	v_mfma_f32_16x16x32_bf16 v[120:123], v[184:187], v[152:155], v[120:123]
	v_mfma_f32_16x16x32_bf16 v[116:119], v[202:205], v[152:155], v[116:119]
	v_mfma_f32_16x16x32_bf16 v[104:107], v[184:187], v[160:163], v[104:107]
	v_mfma_f32_16x16x32_bf16 v[96:99], v[202:205], v[160:163], v[96:99]
	v_mfma_f32_16x16x32_bf16 v[88:91], v[184:187], v[168:171], v[88:91]
	v_mfma_f32_16x16x32_bf16 v[80:83], v[202:205], v[168:171], v[80:83]
	v_mfma_f32_16x16x32_bf16 v[72:75], v[184:187], v[176:179], v[72:75]
	v_mfma_f32_16x16x32_bf16 v[68:71], v[202:205], v[176:179], v[68:71]
	s_barrier
; __device__ __forceinline__ int opaque_tid() { int t = threadIdx.x; asm volatile("" : "+v"(t)); return t; }
; #define PG8_STAGE(bufoff, gbase, voff) do { _Pragma("unroll") for (int _i = 0; _i < 2; ++_i) \
;         __builtin_amdgcn_global_load_lds((const unsigned*)((const char*)(gbase) + (voff)[_i]), (LAS unsigned*)(lds + (bufoff) + ldsw + _i * 8192), 16, 0, 0); } while (0)
; #define PG8_MMA(ai, bj, At, Bt) do { __builtin_amdgcn_s_setprio(1); _Pragma("unroll") for (int m = 0; m < 4; ++m) _Pragma("unroll") for (int n = 0; n < 2; ++n) _Pragma("unroll") for (int k = 0; k < 2; ++k) \
;         acc[ai][bj][m][n] = __builtin_amdgcn_mfma_f32_16x16x32_bf16(Bt[n][k], At[m][k], acc[ai][bj][m][n], 0, 0, 0); __builtin_amdgcn_s_setprio(0); } while (0)
; #define PG8_WAIT_V(n) asm volatile("s_waitcnt vmcnt(" #n ")" ::: "memory")
; #define PG8_WAIT_L(n) asm volatile("s_waitcnt lgkmcnt(" #n ")" ::: "memory")
; #define PG8_BAR __builtin_amdgcn_s_barrier()
; #define PG8_SCHED __builtin_amdgcn_sched_barrier(0)
;     __device__ __forceinline__ void operator()(const f32x4 (&acc)[2][2][4][2], const Unit& u, int wr, int wc, int, int) const {
;         const int ol_ = opaque_tid() & 63, fr = ol_ & 15, fq = ol_ >> 4;
;         const int row0 = u.pm * BM + wr * 64 + fr, col0 = u.pn * BM + wc * 32 + 8 * fq;
;         u32x4 cin[2][4][2];
; #pragma unroll
;         for (int ai = 0; ai < 2; ++ai)
; #pragma unroll
;             for (int m = 0; m < 4; ++m)
; #pragma unroll
;                 for (int bj = 0; bj < 2; ++bj) cin[ai][m][bj] = *(const u32x4*)(C + (size_t)(row0 + ai * HALF + m * 16) * ldc + col0 + bj * HALF);
; template <class Epi, class Sched>
; __device__ __forceinline__ void gemm_phase(LAS unsigned char* lds, const Gemm g, const Sched& S, const Epi& E) {
;     ...
;             PG8_BAR; PG8_WAIT_L(0); PG8_MMA(1, 0, At, B0); PG8_BAR; PG8_SCHED;
;             PG8_STAGE(PG8_SB(1, 1), b3 + hstepB, voffB);
;             PG8_WAIT_V(6); PG8_BAR; PG8_MMA(1, 1, At, B1); PG8_BAR;
	s_setprio 0
	ds_read_b128 v[148:151], v224 offset:49152
	ds_read_b128 v[152:155], v224 offset:50176
	ds_read_b128 v[156:159], v224 offset:51200
	ds_read_b128 v[160:163], v224 offset:52224
	ds_read_b128 v[164:167], v224 offset:53248
	ds_read_b128 v[168:171], v224 offset:54272
	ds_read_b128 v[172:175], v224 offset:55296
	ds_read_b128 v[176:179], v224 offset:56320
	s_add_i32 s25, s52, s30
	v_lshl_add_u64 v[206:207], v[206:207], 0, s[8:9]
	s_mov_b32 m0, s25
	s_nop 0
	global_load_lds_dwordx4 v[206:207], off
	v_lshl_add_u64 v[206:207], v[208:209], 0, s[8:9]
	s_add_i32 m0, s25, 0x2000
	s_nop 0
	global_load_lds_dwordx4 v[206:207], off
	s_mov_b32 m0, s42
	v_lshl_add_u64 v[206:207], v[210:211], 0, s[8:9]
	global_load_lds_dwordx4 v[206:207], off
	v_lshl_add_u64 v[206:207], v[212:213], 0, s[8:9]
	s_mov_b32 m0, s43
	s_nop 0
	global_load_lds_dwordx4 v[206:207], off
	s_add_u32 s20, s20, 0x80080
	s_addc_u32 s21, s21, 0
	s_add_i32 s24, s24, s30
	s_mov_b32 m0, s24
	s_nop 0
	global_load_lds_dwordx4 v2, s[20:21]
	s_add_i32 m0, s24, 0x2000
	s_nop 0
	global_load_lds_dwordx4 v192, s[20:21]
	s_add_i32 s51, s51, 2
	s_add_u32 s6, s6, 0x100
	s_addc_u32 s7, s7, 0
	s_add_u32 s49, s49, 0x100
	s_addc_u32 s50, s50, 0
	s_cmp_gt_u32 s51, 29
	s_waitcnt lgkmcnt(0)
	s_waitcnt vmcnt(6)
	s_setprio 1
	s_barrier
	v_mfma_f32_16x16x32_bf16 v[64:67], v[132:135], v[148:151], v[64:67]
	v_mfma_f32_16x16x32_bf16 v[60:63], v[140:143], v[148:151], v[60:63]
	v_mfma_f32_16x16x32_bf16 v[52:55], v[132:135], v[156:159], v[52:55]
	v_mfma_f32_16x16x32_bf16 v[44:47], v[140:143], v[156:159], v[44:47]
	v_mfma_f32_16x16x32_bf16 v[36:39], v[132:135], v[164:167], v[36:39]
	v_mfma_f32_16x16x32_bf16 v[28:31], v[140:143], v[164:167], v[28:31]
	v_mfma_f32_16x16x32_bf16 v[20:23], v[132:135], v[172:175], v[20:23]
	v_mfma_f32_16x16x32_bf16 v[12:15], v[140:143], v[172:175], v[12:15]
	v_mfma_f32_16x16x32_bf16 v[64:67], v[136:139], v[152:155], v[64:67]
	v_mfma_f32_16x16x32_bf16 v[60:63], v[144:147], v[152:155], v[60:63]
	v_mfma_f32_16x16x32_bf16 v[52:55], v[136:139], v[160:163], v[52:55]
	v_mfma_f32_16x16x32_bf16 v[44:47], v[144:147], v[160:163], v[44:47]
	v_mfma_f32_16x16x32_bf16 v[36:39], v[136:139], v[168:171], v[36:39]
	v_mfma_f32_16x16x32_bf16 v[28:31], v[144:147], v[168:171], v[28:31]
	v_mfma_f32_16x16x32_bf16 v[20:23], v[136:139], v[176:179], v[20:23]
	v_mfma_f32_16x16x32_bf16 v[12:15], v[144:147], v[176:179], v[12:15]
	v_mfma_f32_16x16x32_bf16 v[56:59], v[180:183], v[148:151], v[56:59]
	v_mfma_f32_16x16x32_bf16 v[48:51], v[188:191], v[148:151], v[48:51]
	v_mfma_f32_16x16x32_bf16 v[40:43], v[180:183], v[156:159], v[40:43]
	v_mfma_f32_16x16x32_bf16 v[32:35], v[188:191], v[156:159], v[32:35]
	v_mfma_f32_16x16x32_bf16 v[24:27], v[180:183], v[164:167], v[24:27]
	v_mfma_f32_16x16x32_bf16 v[16:19], v[188:191], v[164:167], v[16:19]
	v_mfma_f32_16x16x32_bf16 v[8:11], v[180:183], v[172:175], v[8:11]
	v_mfma_f32_16x16x32_bf16 v[4:7], v[188:191], v[172:175], v[4:7]
	v_mfma_f32_16x16x32_bf16 v[56:59], v[184:187], v[152:155], v[56:59]
	v_mfma_f32_16x16x32_bf16 v[48:51], v[202:205], v[152:155], v[48:51]
	v_mfma_f32_16x16x32_bf16 v[40:43], v[184:187], v[160:163], v[40:43]
	v_mfma_f32_16x16x32_bf16 v[32:35], v[202:205], v[160:163], v[32:35]
	v_mfma_f32_16x16x32_bf16 v[24:27], v[184:187], v[168:171], v[24:27]
	v_mfma_f32_16x16x32_bf16 v[16:19], v[202:205], v[168:171], v[16:19]
	v_mfma_f32_16x16x32_bf16 v[8:11], v[184:187], v[176:179], v[8:11]
	v_mfma_f32_16x16x32_bf16 v[4:7], v[202:205], v[176:179], v[4:7]
	s_barrier
	s_cbranch_scc0 .LBB0_1396
	s_setprio 0
	v_mov_b32_e32 v133, v0
	s_lshl_b32 s1, s46, 8
	s_add_i32 s1, s1, s38
	v_and_or_b32 v132, v133, 15, s1
	s_lshl_b32 s1, s45, 8
	v_lshrrev_b32_e32 v133, 1, v133
	v_and_or_b32 v133, v133, 24, s1
	v_or_b32_e32 v134, s39, v133
	v_ashrrev_i32_e32 v135, 31, v134
	v_lshlrev_b64 v[202:203], 1, v[134:135]
	v_ashrrev_i32_e32 v133, 31, v132
	v_lshl_add_u64 v[134:135], s[88:89], 0, v[202:203]
	v_lshlrev_b64 v[216:217], 12, v[132:133]
	v_lshl_add_u64 v[136:137], v[134:135], 0, v[216:217]
	global_load_dwordx4 v[226:229], v[136:137], off
	global_load_dwordx4 v[188:191], v[136:137], off offset:256
	v_or_b32_e32 v136, 16, v132
	v_ashrrev_i32_e32 v137, 31, v136
	v_lshlrev_b64 v[222:223], 12, v[136:137]
	v_lshl_add_u64 v[136:137], v[134:135], 0, v[222:223]
	global_load_dwordx4 v[184:187], v[136:137], off
	global_load_dwordx4 v[180:183], v[136:137], off offset:256
	v_or_b32_e32 v136, 32, v132
	v_ashrrev_i32_e32 v137, 31, v136
	v_lshlrev_b64 v[220:221], 12, v[136:137]
	v_lshl_add_u64 v[136:137], v[134:135], 0, v[220:221]
	global_load_dwordx4 v[176:179], v[136:137], off
	global_load_dwordx4 v[168:171], v[136:137], off offset:256
	v_or_b32_e32 v132, 48, v132
	v_ashrrev_i32_e32 v133, 31, v132
	v_lshlrev_b64 v[212:213], 12, v[132:133]
	v_lshl_add_u64 v[132:133], v[134:135], 0, v[212:213]
	global_load_dwordx4 v[172:175], v[132:133], off
	global_load_dwordx4 v[164:167], v[132:133], off offset:256
	s_mov_b64 s[6:7], 0x80000
	v_lshl_add_u64 v[210:211], v[216:217], 0, s[6:7]
	v_lshl_add_u64 v[132:133], v[134:135], 0, v[210:211]
	global_load_dwordx4 v[160:163], v[132:133], off
	global_load_dwordx4 v[156:159], v[132:133], off offset:256
	s_mov_b64 s[6:7], 0x90000
	v_lshl_add_u64 v[208:209], v[216:217], 0, s[6:7]
	v_lshl_add_u64 v[132:133], v[134:135], 0, v[208:209]
	global_load_dwordx4 v[152:155], v[132:133], off
	global_load_dwordx4 v[148:151], v[132:133], off offset:256
	s_mov_b64 s[6:7], 0xa0000
	v_lshl_add_u64 v[206:207], v[216:217], 0, s[6:7]
	v_lshl_add_u64 v[132:133], v[134:135], 0, v[206:207]
	global_load_dwordx4 v[144:147], v[132:133], off
	global_load_dwordx4 v[140:143], v[132:133], off offset:256
	s_mov_b64 s[6:7], 0xb0000
	v_lshl_add_u64 v[204:205], v[216:217], 0, s[6:7]
	v_lshl_add_u64 v[132:133], v[134:135], 0, v[204:205]
	global_load_dwordx4 v[136:139], v[132:133], off
	s_nop 0
	global_load_dwordx4 v[132:135], v[132:133], off offset:256
	s_and_b64 vcc, exec, s[40:41]
	s_mov_b32 s45, s0
	s_mov_b32 s46, s14
	s_mov_b64 s[20:21], s[18:19]
	s_mov_b64 s[6:7], s[4:5]
	s_waitcnt vmcnt(15)
; __device__ __forceinline__ unsigned cvt_pk_bf16(float lo, float hi) { const f32x2 v = {lo, hi}; const bf16v2_ r = __builtin_convertvector(v, bf16v2_); return __builtin_bit_cast(unsigned, r); }
; __device__ __forceinline__ float bflo(unsigned w) { return __uint_as_float(w << 16); }
; __device__ __forceinline__ float bfhi(unsigned w) { return __uint_as_float(w & 0xffff0000u); }
;     __device__ __forceinline__ void operator()(const f32x4 (&acc)[2][2][4][2], const Unit& u, int wr, int wc, int, int) const {
;     ...
;                 for (int bj = 0; bj < 2; ++bj) { const u32x4 c = cin[ai][m][bj]; const f32x4 v0 = acc[ai][bj][m][0], v1 = acc[ai][bj][m][1];
;                     u32x4 w; w.x = cvt_pk_bf16(bflo(c.x) + v0[0], bfhi(c.x) + v0[1]); w.y = cvt_pk_bf16(bflo(c.y) + v0[2], bfhi(c.y) + v0[3]);
;                     w.z = cvt_pk_bf16(bflo(c.z) + v1[0], bfhi(c.z) + v1[1]); w.w = cvt_pk_bf16(bflo(c.w) + v1[2], bfhi(c.w) + v1[3]);
;                     *(u32x4*)(C + (size_t)(row0 + ai * HALF + m * 16) * ldc + col0 + bj * HALF) = w; }
	v_lshlrev_b32_e32 v218, 16, v226
	v_and_b32_e32 v219, 0xffff0000, v226
	v_pk_add_f32 v[128:129], v[128:129], v[218:219]
	v_lshlrev_b32_e32 v218, 16, v227
	v_and_b32_e32 v219, 0xffff0000, v227
	v_pk_add_f32 v[130:131], v[130:131], v[218:219]
	v_cvt_pk_bf16_f32 v128, v128, v129
	v_cvt_pk_bf16_f32 v129, v130, v131
	v_lshlrev_b32_e32 v130, 16, v228
	v_and_b32_e32 v131, 0xffff0000, v228
	v_pk_add_f32 v[124:125], v[124:125], v[130:131]
	s_nop 0
	v_cvt_pk_bf16_f32 v130, v124, v125
	v_lshlrev_b32_e32 v124, 16, v229
	v_and_b32_e32 v125, 0xffff0000, v229
	v_pk_add_f32 v[124:125], v[126:127], v[124:125]
	s_waitcnt vmcnt(14)
	v_lshlrev_b32_e32 v126, 16, v188
	v_and_b32_e32 v127, 0xffff0000, v188
	v_pk_add_f32 v[120:121], v[120:121], v[126:127]
	v_lshlrev_b32_e32 v126, 16, v189
	v_and_b32_e32 v127, 0xffff0000, v189
	v_pk_add_f32 v[122:123], v[122:123], v[126:127]
	v_cvt_pk_bf16_f32 v120, v120, v121
	v_cvt_pk_bf16_f32 v121, v122, v123
	v_lshlrev_b32_e32 v122, 16, v190
	v_and_b32_e32 v123, 0xffff0000, v190
	v_pk_add_f32 v[116:117], v[116:117], v[122:123]
	v_cvt_pk_bf16_f32 v131, v124, v125
	v_cvt_pk_bf16_f32 v122, v116, v117
	v_lshlrev_b32_e32 v116, 16, v191
	v_and_b32_e32 v117, 0xffff0000, v191
	v_pk_add_f32 v[116:117], v[118:119], v[116:117]
	v_lshl_add_u64 v[124:125], s[88:89], 0, v[216:217]
	v_cvt_pk_bf16_f32 v123, v116, v117
	s_waitcnt vmcnt(13)
	v_lshlrev_b32_e32 v116, 16, v184
	v_and_b32_e32 v117, 0xffff0000, v184
	v_pk_add_f32 v[112:113], v[112:113], v[116:117]
	v_lshlrev_b32_e32 v116, 16, v185
	v_and_b32_e32 v117, 0xffff0000, v185
	v_pk_add_f32 v[114:115], v[114:115], v[116:117]
	v_cvt_pk_bf16_f32 v112, v112, v113
	v_cvt_pk_bf16_f32 v113, v114, v115
	v_lshlrev_b32_e32 v114, 16, v186
	v_and_b32_e32 v115, 0xffff0000, v186
	v_pk_add_f32 v[108:109], v[108:109], v[114:115]
	v_lshl_add_u64 v[124:125], v[124:125], 0, v[202:203]
	v_cvt_pk_bf16_f32 v114, v108, v109
	v_lshlrev_b32_e32 v108, 16, v187
	v_and_b32_e32 v109, 0xffff0000, v187
	v_pk_add_f32 v[108:109], v[110:111], v[108:109]
	s_waitcnt vmcnt(12)
	v_lshlrev_b32_e32 v110, 16, v180
	v_and_b32_e32 v111, 0xffff0000, v180
	v_pk_add_f32 v[104:105], v[104:105], v[110:111]
	v_lshlrev_b32_e32 v110, 16, v181
	v_and_b32_e32 v111, 0xffff0000, v181
	v_pk_add_f32 v[106:107], v[106:107], v[110:111]
	v_cvt_pk_bf16_f32 v104, v104, v105
	v_cvt_pk_bf16_f32 v105, v106, v107
	v_lshlrev_b32_e32 v106, 16, v182
	v_and_b32_e32 v107, 0xffff0000, v182
	v_pk_add_f32 v[96:97], v[96:97], v[106:107]
	v_cvt_pk_bf16_f32 v115, v108, v109
	v_cvt_pk_bf16_f32 v106, v96, v97
	v_lshlrev_b32_e32 v96, 16, v183
	v_and_b32_e32 v97, 0xffff0000, v183
	v_pk_add_f32 v[96:97], v[98:99], v[96:97]
	s_waitcnt vmcnt(11)
	v_lshlrev_b32_e32 v98, 16, v177
	v_cvt_pk_bf16_f32 v107, v96, v97
	v_lshlrev_b32_e32 v96, 16, v176
	v_and_b32_e32 v97, 0xffff0000, v176
	v_and_b32_e32 v99, 0xffff0000, v177
	v_pk_add_f32 v[96:97], v[100:101], v[96:97]
	v_pk_add_f32 v[98:99], v[102:103], v[98:99]
	v_cvt_pk_bf16_f32 v96, v96, v97
	v_cvt_pk_bf16_f32 v97, v98, v99
	v_lshlrev_b32_e32 v98, 16, v178
	v_and_b32_e32 v99, 0xffff0000, v178
	v_pk_add_f32 v[92:93], v[92:93], v[98:99]
	v_lshl_add_u64 v[108:109], s[88:89], 0, v[222:223]
	v_cvt_pk_bf16_f32 v98, v92, v93
	v_lshlrev_b32_e32 v92, 16, v179
	v_and_b32_e32 v93, 0xffff0000, v179
	v_pk_add_f32 v[92:93], v[94:95], v[92:93]
	s_waitcnt vmcnt(10)
	v_lshlrev_b32_e32 v94, 16, v168
	v_and_b32_e32 v95, 0xffff0000, v168
	v_pk_add_f32 v[88:89], v[88:89], v[94:95]
	v_lshlrev_b32_e32 v94, 16, v169
	v_and_b32_e32 v95, 0xffff0000, v169
	v_pk_add_f32 v[90:91], v[90:91], v[94:95]
	v_cvt_pk_bf16_f32 v88, v88, v89
	v_cvt_pk_bf16_f32 v89, v90, v91
	v_lshlrev_b32_e32 v90, 16, v170
	v_and_b32_e32 v91, 0xffff0000, v170
	v_pk_add_f32 v[80:81], v[80:81], v[90:91]
	v_cvt_pk_bf16_f32 v99, v92, v93
	v_cvt_pk_bf16_f32 v90, v80, v81
	v_lshlrev_b32_e32 v80, 16, v171
	v_and_b32_e32 v81, 0xffff0000, v171
	v_pk_add_f32 v[80:81], v[82:83], v[80:81]
	s_waitcnt vmcnt(9)
	v_lshlrev_b32_e32 v82, 16, v173
	v_cvt_pk_bf16_f32 v91, v80, v81
	v_lshlrev_b32_e32 v80, 16, v172
	v_and_b32_e32 v81, 0xffff0000, v172
	v_and_b32_e32 v83, 0xffff0000, v173
	v_pk_add_f32 v[80:81], v[84:85], v[80:81]
	v_pk_add_f32 v[82:83], v[86:87], v[82:83]
	v_cvt_pk_bf16_f32 v80, v80, v81
	v_cvt_pk_bf16_f32 v81, v82, v83
	v_lshlrev_b32_e32 v82, 16, v174
	v_and_b32_e32 v83, 0xffff0000, v174
	v_pk_add_f32 v[76:77], v[76:77], v[82:83]
	v_lshl_add_u64 v[92:93], s[88:89], 0, v[220:221]
	v_cvt_pk_bf16_f32 v82, v76, v77
	v_lshlrev_b32_e32 v76, 16, v175
	v_and_b32_e32 v77, 0xffff0000, v175
	v_pk_add_f32 v[76:77], v[78:79], v[76:77]
	s_waitcnt vmcnt(8)
	v_lshlrev_b32_e32 v78, 16, v164
	v_and_b32_e32 v79, 0xffff0000, v164
	v_pk_add_f32 v[72:73], v[72:73], v[78:79]
	v_lshlrev_b32_e32 v78, 16, v165
	v_and_b32_e32 v79, 0xffff0000, v165
	v_pk_add_f32 v[74:75], v[74:75], v[78:79]
	v_cvt_pk_bf16_f32 v72, v72, v73
	v_cvt_pk_bf16_f32 v73, v74, v75
	v_lshlrev_b32_e32 v74, 16, v166
	v_and_b32_e32 v75, 0xffff0000, v166
	v_pk_add_f32 v[68:69], v[68:69], v[74:75]
	v_cvt_pk_bf16_f32 v83, v76, v77
	v_cvt_pk_bf16_f32 v74, v68, v69
	v_lshlrev_b32_e32 v68, 16, v167
	v_and_b32_e32 v69, 0xffff0000, v167
	v_pk_add_f32 v[68:69], v[70:71], v[68:69]
	v_lshl_add_u64 v[76:77], s[88:89], 0, v[212:213]
	v_cvt_pk_bf16_f32 v75, v68, v69
	s_waitcnt vmcnt(7)
	v_lshlrev_b32_e32 v68, 16, v160
	v_and_b32_e32 v69, 0xffff0000, v160
	v_pk_add_f32 v[64:65], v[64:65], v[68:69]
	v_lshlrev_b32_e32 v68, 16, v161
	v_and_b32_e32 v69, 0xffff0000, v161
	v_pk_add_f32 v[66:67], v[66:67], v[68:69]
	v_cvt_pk_bf16_f32 v64, v64, v65
	v_cvt_pk_bf16_f32 v65, v66, v67
	v_lshlrev_b32_e32 v66, 16, v162
	v_and_b32_e32 v67, 0xffff0000, v162
	v_pk_add_f32 v[60:61], v[60:61], v[66:67]
	v_lshl_add_u64 v[108:109], v[108:109], 0, v[202:203]
	v_cvt_pk_bf16_f32 v66, v60, v61
	v_lshlrev_b32_e32 v60, 16, v163
	v_and_b32_e32 v61, 0xffff0000, v163
	v_pk_add_f32 v[60:61], v[62:63], v[60:61]
	s_waitcnt vmcnt(6)
; __device__ __forceinline__ unsigned cvt_pk_bf16(float lo, float hi) { const f32x2 v = {lo, hi}; const bf16v2_ r = __builtin_convertvector(v, bf16v2_); return __builtin_bit_cast(unsigned, r); }
; __device__ __forceinline__ float bflo(unsigned w) { return __uint_as_float(w << 16); }
; __device__ __forceinline__ float bfhi(unsigned w) { return __uint_as_float(w & 0xffff0000u); }
;     __device__ __forceinline__ void operator()(const f32x4 (&acc)[2][2][4][2], const Unit& u, int wr, int wc, int, int) const {
;     ...
;                 for (int bj = 0; bj < 2; ++bj) { const u32x4 c = cin[ai][m][bj]; const f32x4 v0 = acc[ai][bj][m][0], v1 = acc[ai][bj][m][1];
;                     u32x4 w; w.x = cvt_pk_bf16(bflo(c.x) + v0[0], bfhi(c.x) + v0[1]); w.y = cvt_pk_bf16(bflo(c.y) + v0[2], bfhi(c.y) + v0[3]);
;                     w.z = cvt_pk_bf16(bflo(c.z) + v1[0], bfhi(c.z) + v1[1]); w.w = cvt_pk_bf16(bflo(c.w) + v1[2], bfhi(c.w) + v1[3]);
;                     *(u32x4*)(C + (size_t)(row0 + ai * HALF + m * 16) * ldc + col0 + bj * HALF) = w; }
	v_lshlrev_b32_e32 v62, 16, v156
	v_and_b32_e32 v63, 0xffff0000, v156
	v_pk_add_f32 v[56:57], v[56:57], v[62:63]
	v_lshlrev_b32_e32 v62, 16, v157
	v_and_b32_e32 v63, 0xffff0000, v157
	v_pk_add_f32 v[58:59], v[58:59], v[62:63]
	v_cvt_pk_bf16_f32 v56, v56, v57
	v_cvt_pk_bf16_f32 v57, v58, v59
	v_lshlrev_b32_e32 v58, 16, v158
	v_and_b32_e32 v59, 0xffff0000, v158
	v_pk_add_f32 v[48:49], v[48:49], v[58:59]
	v_cvt_pk_bf16_f32 v67, v60, v61
	v_cvt_pk_bf16_f32 v58, v48, v49
	v_lshlrev_b32_e32 v48, 16, v159
	v_and_b32_e32 v49, 0xffff0000, v159
	v_pk_add_f32 v[48:49], v[50:51], v[48:49]
	s_waitcnt vmcnt(5)
	v_lshlrev_b32_e32 v50, 16, v153
	v_cvt_pk_bf16_f32 v59, v48, v49
	v_lshlrev_b32_e32 v48, 16, v152
	v_and_b32_e32 v49, 0xffff0000, v152
	v_and_b32_e32 v51, 0xffff0000, v153
	v_pk_add_f32 v[48:49], v[52:53], v[48:49]
	v_pk_add_f32 v[50:51], v[54:55], v[50:51]
	v_cvt_pk_bf16_f32 v48, v48, v49
	v_cvt_pk_bf16_f32 v49, v50, v51
	v_lshlrev_b32_e32 v50, 16, v154
	v_and_b32_e32 v51, 0xffff0000, v154
	v_pk_add_f32 v[44:45], v[44:45], v[50:51]
	v_lshl_add_u64 v[60:61], s[88:89], 0, v[210:211]
	v_cvt_pk_bf16_f32 v50, v44, v45
	v_lshlrev_b32_e32 v44, 16, v155
	v_and_b32_e32 v45, 0xffff0000, v155
	v_pk_add_f32 v[44:45], v[46:47], v[44:45]
	s_waitcnt vmcnt(4)
	v_lshlrev_b32_e32 v46, 16, v148
	v_and_b32_e32 v47, 0xffff0000, v148
	v_pk_add_f32 v[40:41], v[40:41], v[46:47]
	v_lshlrev_b32_e32 v46, 16, v149
	v_and_b32_e32 v47, 0xffff0000, v149
	v_pk_add_f32 v[42:43], v[42:43], v[46:47]
	v_cvt_pk_bf16_f32 v40, v40, v41
	v_cvt_pk_bf16_f32 v41, v42, v43
	v_lshlrev_b32_e32 v42, 16, v150
	v_and_b32_e32 v43, 0xffff0000, v150
	v_pk_add_f32 v[32:33], v[32:33], v[42:43]
	v_cvt_pk_bf16_f32 v51, v44, v45
	v_cvt_pk_bf16_f32 v42, v32, v33
	v_lshlrev_b32_e32 v32, 16, v151
	v_and_b32_e32 v33, 0xffff0000, v151
	v_pk_add_f32 v[32:33], v[34:35], v[32:33]
	s_waitcnt vmcnt(3)
	v_lshlrev_b32_e32 v34, 16, v145
	v_cvt_pk_bf16_f32 v43, v32, v33
	v_lshlrev_b32_e32 v32, 16, v144
	v_and_b32_e32 v33, 0xffff0000, v144
	v_and_b32_e32 v35, 0xffff0000, v145
	v_pk_add_f32 v[32:33], v[36:37], v[32:33]
	v_pk_add_f32 v[34:35], v[38:39], v[34:35]
	v_cvt_pk_bf16_f32 v32, v32, v33
	v_cvt_pk_bf16_f32 v33, v34, v35
	v_lshlrev_b32_e32 v34, 16, v146
	v_and_b32_e32 v35, 0xffff0000, v146
	v_pk_add_f32 v[28:29], v[28:29], v[34:35]
	v_lshl_add_u64 v[44:45], s[88:89], 0, v[208:209]
	v_cvt_pk_bf16_f32 v34, v28, v29
	v_lshlrev_b32_e32 v28, 16, v147
	v_and_b32_e32 v29, 0xffff0000, v147
	v_pk_add_f32 v[28:29], v[30:31], v[28:29]
	s_waitcnt vmcnt(2)
	v_lshlrev_b32_e32 v30, 16, v140
	v_and_b32_e32 v31, 0xffff0000, v140
	v_pk_add_f32 v[24:25], v[24:25], v[30:31]
	v_lshlrev_b32_e32 v30, 16, v141
	v_and_b32_e32 v31, 0xffff0000, v141
	v_pk_add_f32 v[26:27], v[26:27], v[30:31]
	v_cvt_pk_bf16_f32 v24, v24, v25
	v_cvt_pk_bf16_f32 v25, v26, v27
	v_lshlrev_b32_e32 v26, 16, v142
	v_and_b32_e32 v27, 0xffff0000, v142
	v_pk_add_f32 v[16:17], v[16:17], v[26:27]
	v_cvt_pk_bf16_f32 v35, v28, v29
	v_cvt_pk_bf16_f32 v26, v16, v17
	v_lshlrev_b32_e32 v16, 16, v143
	v_and_b32_e32 v17, 0xffff0000, v143
	v_pk_add_f32 v[16:17], v[18:19], v[16:17]
	s_waitcnt vmcnt(1)
	v_lshlrev_b32_e32 v18, 16, v137
	v_cvt_pk_bf16_f32 v27, v16, v17
	v_lshlrev_b32_e32 v16, 16, v136
	v_and_b32_e32 v17, 0xffff0000, v136
	v_and_b32_e32 v19, 0xffff0000, v137
	v_pk_add_f32 v[16:17], v[20:21], v[16:17]
	v_pk_add_f32 v[18:19], v[22:23], v[18:19]
	v_cvt_pk_bf16_f32 v16, v16, v17
	v_cvt_pk_bf16_f32 v17, v18, v19
	v_lshlrev_b32_e32 v18, 16, v138
	v_and_b32_e32 v19, 0xffff0000, v138
	v_pk_add_f32 v[12:13], v[12:13], v[18:19]
	v_lshl_add_u64 v[28:29], s[88:89], 0, v[206:207]
	v_cvt_pk_bf16_f32 v18, v12, v13
	v_lshlrev_b32_e32 v12, 16, v139
	v_and_b32_e32 v13, 0xffff0000, v139
	v_pk_add_f32 v[12:13], v[14:15], v[12:13]
	s_waitcnt vmcnt(0)
; __device__ __forceinline__ unsigned cvt_pk_bf16(float lo, float hi) { const f32x2 v = {lo, hi}; const bf16v2_ r = __builtin_convertvector(v, bf16v2_); return __builtin_bit_cast(unsigned, r); }
; __device__ __forceinline__ float bflo(unsigned w) { return __uint_as_float(w << 16); }
; __device__ __forceinline__ float bfhi(unsigned w) { return __uint_as_float(w & 0xffff0000u); }
;     __device__ __forceinline__ void operator()(const f32x4 (&acc)[2][2][4][2], const Unit& u, int wr, int wc, int, int) const {
;     ...
;                 for (int bj = 0; bj < 2; ++bj) cin[ai][m][bj] = *(const u32x4*)(C + (size_t)(row0 + ai * HALF + m * 16) * ldc + col0 + bj * HALF);
; #pragma unroll
;         for (int ai = 0; ai < 2; ++ai)
; #pragma unroll
;             for (int m = 0; m < 4; ++m)
; #pragma unroll
;                 for (int bj = 0; bj < 2; ++bj) { const u32x4 c = cin[ai][m][bj]; const f32x4 v0 = acc[ai][bj][m][0], v1 = acc[ai][bj][m][1];
;                     u32x4 w; w.x = cvt_pk_bf16(bflo(c.x) + v0[0], bfhi(c.x) + v0[1]); w.y = cvt_pk_bf16(bflo(c.y) + v0[2], bfhi(c.y) + v0[3]);
;                     w.z = cvt_pk_bf16(bflo(c.z) + v1[0], bfhi(c.z) + v1[1]); w.w = cvt_pk_bf16(bflo(c.w) + v1[2], bfhi(c.w) + v1[3]);
;                     *(u32x4*)(C + (size_t)(row0 + ai * HALF + m * 16) * ldc + col0 + bj * HALF) = w; }
	v_lshlrev_b32_e32 v14, 16, v132
	v_and_b32_e32 v15, 0xffff0000, v132
	v_pk_add_f32 v[8:9], v[8:9], v[14:15]
	v_lshlrev_b32_e32 v14, 16, v133
	v_and_b32_e32 v15, 0xffff0000, v133
	v_pk_add_f32 v[10:11], v[10:11], v[14:15]
	v_cvt_pk_bf16_f32 v8, v8, v9
	v_cvt_pk_bf16_f32 v9, v10, v11
	v_lshlrev_b32_e32 v10, 16, v134
	v_and_b32_e32 v11, 0xffff0000, v134
	v_pk_add_f32 v[4:5], v[4:5], v[10:11]
	v_cvt_pk_bf16_f32 v19, v12, v13
	v_cvt_pk_bf16_f32 v10, v4, v5
	v_lshlrev_b32_e32 v4, 16, v135
	v_and_b32_e32 v5, 0xffff0000, v135
	v_lshl_add_u64 v[12:13], s[88:89], 0, v[204:205]
	v_pk_add_f32 v[4:5], v[6:7], v[4:5]
	v_lshl_add_u64 v[92:93], v[92:93], 0, v[202:203]
	v_lshl_add_u64 v[76:77], v[76:77], 0, v[202:203]
	v_lshl_add_u64 v[60:61], v[60:61], 0, v[202:203]
	v_lshl_add_u64 v[44:45], v[44:45], 0, v[202:203]
	v_lshl_add_u64 v[28:29], v[28:29], 0, v[202:203]
	v_lshl_add_u64 v[12:13], v[12:13], 0, v[202:203]
	v_cvt_pk_bf16_f32 v11, v4, v5
	global_store_dwordx4 v[124:125], v[128:131], off
	global_store_dwordx4 v[124:125], v[120:123], off offset:256
	global_store_dwordx4 v[108:109], v[112:115], off
	global_store_dwordx4 v[108:109], v[104:107], off offset:256
	global_store_dwordx4 v[92:93], v[96:99], off
	global_store_dwordx4 v[92:93], v[88:91], off offset:256
	global_store_dwordx4 v[76:77], v[80:83], off
	global_store_dwordx4 v[76:77], v[72:75], off offset:256
	global_store_dwordx4 v[60:61], v[64:67], off
	global_store_dwordx4 v[60:61], v[56:59], off offset:256
	global_store_dwordx4 v[44:45], v[48:51], off
	global_store_dwordx4 v[44:45], v[40:43], off offset:256
	global_store_dwordx4 v[28:29], v[32:35], off
	global_store_dwordx4 v[28:29], v[24:27], off offset:256
	global_store_dwordx4 v[12:13], v[16:19], off
	global_store_dwordx4 v[12:13], v[8:11], off offset:256
	v_subrev_u32_e32 v226, s88, v124
	v_bfe_u32 v227, v226, 4, 8
	v_lshrrev_b32_e32 v226, 12, v226
	v_and_b32_e32 v228, 15, v227
	v_lshrrev_b32_e32 v227, 5, v227
	v_lshl_or_b32 v227, v227, 4, v228
	v_lshlrev_b32_e32 v227, 17, v227
	v_lshl_add_u32 v226, v226, 2, v227
	v_add_u32_e32 v226, 0x1e000000, v226
	v_mov_b32_e32 v188, 0
	v_dot2c_f32_bf16_e32 v188, v128, v128
	v_dot2c_f32_bf16_e32 v188, v129, v129
	v_dot2c_f32_bf16_e32 v188, v130, v130
	v_dot2c_f32_bf16_e32 v188, v131, v131
	v_dot2c_f32_bf16_e32 v188, v120, v120
	v_dot2c_f32_bf16_e32 v188, v121, v121
	v_dot2c_f32_bf16_e32 v188, v122, v122
	v_dot2c_f32_bf16_e32 v188, v123, v123
	s_nop 2
	global_store_dword v226, v188, s[88:89]
	v_mov_b32_e32 v189, 0
	v_dot2c_f32_bf16_e32 v189, v112, v112
	v_dot2c_f32_bf16_e32 v189, v113, v113
	v_dot2c_f32_bf16_e32 v189, v114, v114
	v_dot2c_f32_bf16_e32 v189, v115, v115
	v_dot2c_f32_bf16_e32 v189, v104, v104
	v_dot2c_f32_bf16_e32 v189, v105, v105
	v_dot2c_f32_bf16_e32 v189, v106, v106
	v_dot2c_f32_bf16_e32 v189, v107, v107
	s_nop 2
	global_store_dword v226, v189, s[88:89] offset:64
	v_mov_b32_e32 v188, 0
	v_dot2c_f32_bf16_e32 v188, v96, v96
	v_dot2c_f32_bf16_e32 v188, v97, v97
	v_dot2c_f32_bf16_e32 v188, v98, v98
	v_dot2c_f32_bf16_e32 v188, v99, v99
	v_dot2c_f32_bf16_e32 v188, v88, v88
	v_dot2c_f32_bf16_e32 v188, v89, v89
	v_dot2c_f32_bf16_e32 v188, v90, v90
	v_dot2c_f32_bf16_e32 v188, v91, v91
	s_nop 2
	global_store_dword v226, v188, s[88:89] offset:128
	v_mov_b32_e32 v189, 0
	v_dot2c_f32_bf16_e32 v189, v80, v80
	v_dot2c_f32_bf16_e32 v189, v81, v81
	v_dot2c_f32_bf16_e32 v189, v82, v82
	v_dot2c_f32_bf16_e32 v189, v83, v83
	v_dot2c_f32_bf16_e32 v189, v72, v72
	v_dot2c_f32_bf16_e32 v189, v73, v73
	v_dot2c_f32_bf16_e32 v189, v74, v74
	v_dot2c_f32_bf16_e32 v189, v75, v75
	s_nop 2
	global_store_dword v226, v189, s[88:89] offset:192
	v_mov_b32_e32 v188, 0
	v_dot2c_f32_bf16_e32 v188, v64, v64
	v_dot2c_f32_bf16_e32 v188, v65, v65
	v_dot2c_f32_bf16_e32 v188, v66, v66
	v_dot2c_f32_bf16_e32 v188, v67, v67
	v_dot2c_f32_bf16_e32 v188, v56, v56
	v_dot2c_f32_bf16_e32 v188, v57, v57
	v_dot2c_f32_bf16_e32 v188, v58, v58
	v_dot2c_f32_bf16_e32 v188, v59, v59
	s_nop 2
	global_store_dword v226, v188, s[88:89] offset:512
	v_mov_b32_e32 v189, 0
	v_dot2c_f32_bf16_e32 v189, v48, v48
	v_dot2c_f32_bf16_e32 v189, v49, v49
	v_dot2c_f32_bf16_e32 v189, v50, v50
	v_dot2c_f32_bf16_e32 v189, v51, v51
	v_dot2c_f32_bf16_e32 v189, v40, v40
	v_dot2c_f32_bf16_e32 v189, v41, v41
	v_dot2c_f32_bf16_e32 v189, v42, v42
	v_dot2c_f32_bf16_e32 v189, v43, v43
	s_nop 2
	global_store_dword v226, v189, s[88:89] offset:576
	v_mov_b32_e32 v188, 0
	v_dot2c_f32_bf16_e32 v188, v32, v32
	v_dot2c_f32_bf16_e32 v188, v33, v33
	v_dot2c_f32_bf16_e32 v188, v34, v34
	v_dot2c_f32_bf16_e32 v188, v35, v35
	v_dot2c_f32_bf16_e32 v188, v24, v24
	v_dot2c_f32_bf16_e32 v188, v25, v25
	v_dot2c_f32_bf16_e32 v188, v26, v26
	v_dot2c_f32_bf16_e32 v188, v27, v27
	s_nop 2
	global_store_dword v226, v188, s[88:89] offset:640
	v_mov_b32_e32 v189, 0
	v_dot2c_f32_bf16_e32 v189, v16, v16
	v_dot2c_f32_bf16_e32 v189, v17, v17
	v_dot2c_f32_bf16_e32 v189, v18, v18
	v_dot2c_f32_bf16_e32 v189, v19, v19
	v_dot2c_f32_bf16_e32 v189, v8, v8
	v_dot2c_f32_bf16_e32 v189, v9, v9
	v_dot2c_f32_bf16_e32 v189, v10, v10
	v_dot2c_f32_bf16_e32 v189, v11, v11
	s_nop 2
	global_store_dword v226, v189, s[88:89] offset:704
	s_cbranch_vccz .LBB0_1389
	s_waitcnt vmcnt(0)
	s_cmpk_gt_u32 s2, 0xff
	s_cbranch_scc1 .LBB0_1400
	s_barrier

; #define PG8_STAGE(bufoff, gbase, voff) do { _Pragma("unroll") for (int _i = 0; _i < 2; ++_i) \
;         __builtin_amdgcn_global_load_lds((const unsigned*)((const char*)(gbase) + (voff)[_i]), (LAS unsigned*)(lds + (bufoff) + ldsw + _i * 8192), 16, 0, 0); } while (0)
; #define PG8_LDA(dst, b, h) do { _Pragma("unroll") for (int m = 0; m < 4; ++m) _Pragma("unroll") for (int k = 0; k < 2; ++k) dst[m][k] = *(const LAS bf16x8*)(lds + PG8_SA(b, h) + aoff + m * 2048 + k * 1024); } while (0)
; #define PG8_LDB(dst, b, h) do { _Pragma("unroll") for (int n = 0; n < 2; ++n) _Pragma("unroll") for (int k = 0; k < 2; ++k) dst[n][k] = *(const LAS bf16x8*)(lds + PG8_SB(b, h) + boff + n * 2048 + k * 1024); } while (0)
; #define PG8_MMA(ai, bj, At, Bt) do { __builtin_amdgcn_s_setprio(1); _Pragma("unroll") for (int m = 0; m < 4; ++m) _Pragma("unroll") for (int n = 0; n < 2; ++n) _Pragma("unroll") for (int k = 0; k < 2; ++k) \
;         acc[ai][bj][m][n] = __builtin_amdgcn_mfma_f32_16x16x32_bf16(Bt[n][k], At[m][k], acc[ai][bj][m][n], 0, 0, 0); __builtin_amdgcn_s_setprio(0); } while (0)
; #define PG8_WAIT_V(n) asm volatile("s_waitcnt vmcnt(" #n ")" ::: "memory")
; #define PG8_WAIT_L(n) asm volatile("s_waitcnt lgkmcnt(" #n ")" ::: "memory")
; #define PG8_BAR __builtin_amdgcn_s_barrier()
; #define PG8_SCHED __builtin_amdgcn_sched_barrier(0)
; template <class Epi, class Sched>
; __device__ __forceinline__ void gemm_phase(LAS unsigned char* lds, const Gemm g, const Sched& S, const Epi& E) {
;     ...
;             PG8_LDB(B0, 0, 0); PG8_SCHED; PG8_LDA(At, 0, 0); PG8_STAGE(PG8_SA(1, 1), a1 + hstepA, voffA);
;             PG8_WAIT_L(8); PG8_BAR; PG8_WAIT_L(0); PG8_MMA(0, 0, At, B0); PG8_BAR; PG8_SCHED;
;             PG8_LDB(B1, 0, 1); PG8_STAGE(PG8_SB(0, 0), b2, voffB);
;             PG8_BAR; PG8_WAIT_L(0); PG8_MMA(0, 1, At, B1); PG8_BAR;
;             PG8_LDA(At, 0, 1); PG8_STAGE(PG8_SA(0, 0), a2, voffA);
;             PG8_BAR; PG8_WAIT_L(0); PG8_MMA(1, 0, At, B0); PG8_BAR; PG8_SCHED;
;             PG8_STAGE(PG8_SB(0, 1), b2 + hstepB, voffB);
;             PG8_WAIT_V(6); PG8_BAR; PG8_MMA(1, 1, At, B1); PG8_BAR;
.LBB0_1666:
	s_setprio 0
	s_add_u32 s14, s6, 0x100
	s_addc_u32 s15, s7, 0
	s_add_i32 s45, 0, 0x10000
	v_add_u32_e32 v144, s45, v1
	ds_read_b128 v[132:135], v144
	ds_read_b128 v[136:139], v144 offset:1024
	ds_read_b128 v[140:143], v144 offset:2048
	ds_read_b128 v[144:147], v144 offset:3072
	s_cmpk_eq_i32 s44, 0x54
	s_cselect_b32 s21, s1, s15
	s_cselect_b32 s20, s0, s14
	s_cselect_b32 s19, s5, s43
	s_cselect_b32 s18, s4, s42
	ds_read_b128 v[148:151], v224
	ds_read_b128 v[152:155], v224 offset:1024
	ds_read_b128 v[156:159], v224 offset:2048
	ds_read_b128 v[160:163], v224 offset:3072
	ds_read_b128 v[164:167], v224 offset:4096
	ds_read_b128 v[168:171], v224 offset:5120
	ds_read_b128 v[172:175], v224 offset:6144
	ds_read_b128 v[176:179], v224 offset:7168
	s_add_i32 s51, 0, 0x14000
	v_add_u32_e32 v202, s51, v1
	ds_read_b128 v[180:183], v202
	ds_read_b128 v[184:187], v202 offset:1024
	ds_read_b128 v[188:191], v202 offset:2048
	ds_read_b128 v[202:205], v202 offset:3072
	s_add_i32 m0, s29, 0xc000
	s_nop 0
	global_load_lds_dwordx4 v198, s[6:7]
	s_add_i32 m0, s29, 0xe000
	s_nop 0
	global_load_lds_dwordx4 v200, s[6:7]
	s_waitcnt lgkmcnt(0)
	s_setprio 1
	s_barrier
	v_mfma_f32_16x16x32_bf16 v[128:131], v[132:135], v[148:151], v[128:131]
	v_mfma_f32_16x16x32_bf16 v[124:127], v[140:143], v[148:151], v[124:127]
	v_mfma_f32_16x16x32_bf16 v[112:115], v[132:135], v[156:159], v[112:115]
	v_mfma_f32_16x16x32_bf16 v[108:111], v[140:143], v[156:159], v[108:111]
	v_mfma_f32_16x16x32_bf16 v[100:103], v[132:135], v[164:167], v[100:103]
	v_mfma_f32_16x16x32_bf16 v[92:95], v[140:143], v[164:167], v[92:95]
	v_mfma_f32_16x16x32_bf16 v[84:87], v[132:135], v[172:175], v[84:87]
	v_mfma_f32_16x16x32_bf16 v[76:79], v[140:143], v[172:175], v[76:79]
	v_mfma_f32_16x16x32_bf16 v[128:131], v[136:139], v[152:155], v[128:131]
	v_mfma_f32_16x16x32_bf16 v[124:127], v[144:147], v[152:155], v[124:127]
	v_mfma_f32_16x16x32_bf16 v[112:115], v[136:139], v[160:163], v[112:115]
	v_mfma_f32_16x16x32_bf16 v[108:111], v[144:147], v[160:163], v[108:111]
	v_mfma_f32_16x16x32_bf16 v[100:103], v[136:139], v[168:171], v[100:103]
	v_mfma_f32_16x16x32_bf16 v[92:95], v[144:147], v[168:171], v[92:95]
	v_mfma_f32_16x16x32_bf16 v[84:87], v[136:139], v[176:179], v[84:87]
	v_mfma_f32_16x16x32_bf16 v[76:79], v[144:147], v[176:179], v[76:79]
	v_mfma_f32_16x16x32_bf16 v[120:123], v[180:183], v[148:151], v[120:123]
	v_mfma_f32_16x16x32_bf16 v[116:119], v[188:191], v[148:151], v[116:119]
	v_mfma_f32_16x16x32_bf16 v[104:107], v[180:183], v[156:159], v[104:107]
	v_mfma_f32_16x16x32_bf16 v[96:99], v[188:191], v[156:159], v[96:99]
	v_mfma_f32_16x16x32_bf16 v[88:91], v[180:183], v[164:167], v[88:91]
	v_mfma_f32_16x16x32_bf16 v[80:83], v[188:191], v[164:167], v[80:83]
	v_mfma_f32_16x16x32_bf16 v[72:75], v[180:183], v[172:175], v[72:75]
	v_mfma_f32_16x16x32_bf16 v[68:71], v[188:191], v[172:175], v[68:71]
	v_mfma_f32_16x16x32_bf16 v[120:123], v[184:187], v[152:155], v[120:123]
	v_mfma_f32_16x16x32_bf16 v[116:119], v[202:205], v[152:155], v[116:119]
	v_mfma_f32_16x16x32_bf16 v[104:107], v[184:187], v[160:163], v[104:107]
	v_mfma_f32_16x16x32_bf16 v[96:99], v[202:205], v[160:163], v[96:99]
	v_mfma_f32_16x16x32_bf16 v[88:91], v[184:187], v[168:171], v[88:91]
	v_mfma_f32_16x16x32_bf16 v[80:83], v[202:205], v[168:171], v[80:83]
	v_mfma_f32_16x16x32_bf16 v[72:75], v[184:187], v[176:179], v[72:75]
	v_mfma_f32_16x16x32_bf16 v[68:71], v[202:205], v[176:179], v[68:71]
	s_barrier
	s_setprio 0
	ds_read_b128 v[148:151], v224 offset:16384
	ds_read_b128 v[152:155], v224 offset:17408
	ds_read_b128 v[156:159], v224 offset:18432
	ds_read_b128 v[160:163], v224 offset:19456
	ds_read_b128 v[164:167], v224 offset:20480
	ds_read_b128 v[168:171], v224 offset:21504
	ds_read_b128 v[172:175], v224 offset:22528
	ds_read_b128 v[176:179], v224 offset:23552
	s_add_i32 s6, s45, s28
	v_lshl_add_u64 v[206:207], s[18:19], 0, v[2:3]
	s_mov_b32 m0, s6
	s_nop 0
	global_load_lds_dwordx4 v[206:207], off
	v_lshl_add_u64 v[208:209], s[18:19], 0, v[192:193]
	s_add_i32 m0, s6, 0x2000
	s_nop 0
	global_load_lds_dwordx4 v[208:209], off
	s_mov_b32 m0, s29
	v_lshl_add_u64 v[210:211], s[20:21], 0, v[196:197]
	global_load_lds_dwordx4 v[210:211], off
	v_lshl_add_u64 v[212:213], s[20:21], 0, v[194:195]
	s_mov_b32 m0, s30
	s_nop 0
	global_load_lds_dwordx4 v[212:213], off
	s_add_u32 s6, s18, 0x160000
	s_addc_u32 s7, s19, 0
	s_add_i32 s45, s51, s28
	s_mov_b32 m0, s45
	s_nop 0
	global_load_lds_dwordx4 v2, s[6:7]
	s_add_i32 m0, s45, 0x2000
	s_nop 0
	global_load_lds_dwordx4 v192, s[6:7]
	s_waitcnt lgkmcnt(0)
	s_waitcnt vmcnt(6)
	s_setprio 1
	s_barrier
; #define PG8_STAGE(bufoff, gbase, voff) do { _Pragma("unroll") for (int _i = 0; _i < 2; ++_i) \
;         __builtin_amdgcn_global_load_lds((const unsigned*)((const char*)(gbase) + (voff)[_i]), (LAS unsigned*)(lds + (bufoff) + ldsw + _i * 8192), 16, 0, 0); } while (0)
; #define PG8_LDA(dst, b, h) do { _Pragma("unroll") for (int m = 0; m < 4; ++m) _Pragma("unroll") for (int k = 0; k < 2; ++k) dst[m][k] = *(const LAS bf16x8*)(lds + PG8_SA(b, h) + aoff + m * 2048 + k * 1024); } while (0)
; #define PG8_LDB(dst, b, h) do { _Pragma("unroll") for (int n = 0; n < 2; ++n) _Pragma("unroll") for (int k = 0; k < 2; ++k) dst[n][k] = *(const LAS bf16x8*)(lds + PG8_SB(b, h) + boff + n * 2048 + k * 1024); } while (0)
; #define PG8_MMA(ai, bj, At, Bt) do { __builtin_amdgcn_s_setprio(1); _Pragma("unroll") for (int m = 0; m < 4; ++m) _Pragma("unroll") for (int n = 0; n < 2; ++n) _Pragma("unroll") for (int k = 0; k < 2; ++k) \
;         acc[ai][bj][m][n] = __builtin_amdgcn_mfma_f32_16x16x32_bf16(Bt[n][k], At[m][k], acc[ai][bj][m][n], 0, 0, 0); __builtin_amdgcn_s_setprio(0); } while (0)
; #define PG8_WAIT_V(n) asm volatile("s_waitcnt vmcnt(" #n ")" ::: "memory")
; #define PG8_WAIT_L(n) asm volatile("s_waitcnt lgkmcnt(" #n ")" ::: "memory")
; #define PG8_BAR __builtin_amdgcn_s_barrier()
; #define PG8_SCHED __builtin_amdgcn_sched_barrier(0)
; template <class Epi, class Sched>
; __device__ __forceinline__ void gemm_phase(LAS unsigned char* lds, const Gemm g, const Sched& S, const Epi& E) {
;     ...
;             PG8_WAIT_V(6); PG8_BAR; PG8_MMA(1, 1, At, B1); PG8_BAR;
;             PG8_LDB(B0, 1, 0); PG8_SCHED; PG8_LDA(At, 1, 0); PG8_STAGE(PG8_SA(0, 1), a2 + hstepA, voffA);
;             PG8_WAIT_L(8); PG8_BAR; PG8_WAIT_L(0); PG8_MMA(0, 0, At, B0); PG8_BAR; PG8_SCHED;
;             PG8_LDB(B1, 1, 1); PG8_STAGE(PG8_SB(1, 0), b3, voffB);
;             PG8_BAR; PG8_WAIT_L(0); PG8_MMA(0, 1, At, B1); PG8_BAR;
;             PG8_LDA(At, 1, 1); PG8_STAGE(PG8_SA(1, 0), a3, voffA);
;             PG8_BAR; PG8_WAIT_L(0); PG8_MMA(1, 0, At, B0); PG8_BAR; PG8_SCHED;
	v_mfma_f32_16x16x32_bf16 v[64:67], v[132:135], v[148:151], v[64:67]
	v_mfma_f32_16x16x32_bf16 v[60:63], v[140:143], v[148:151], v[60:63]
	v_mfma_f32_16x16x32_bf16 v[52:55], v[132:135], v[156:159], v[52:55]
	v_mfma_f32_16x16x32_bf16 v[44:47], v[140:143], v[156:159], v[44:47]
	v_mfma_f32_16x16x32_bf16 v[36:39], v[132:135], v[164:167], v[36:39]
	v_mfma_f32_16x16x32_bf16 v[28:31], v[140:143], v[164:167], v[28:31]
	v_mfma_f32_16x16x32_bf16 v[20:23], v[132:135], v[172:175], v[20:23]
	v_mfma_f32_16x16x32_bf16 v[12:15], v[140:143], v[172:175], v[12:15]
	v_mfma_f32_16x16x32_bf16 v[64:67], v[136:139], v[152:155], v[64:67]
	v_mfma_f32_16x16x32_bf16 v[60:63], v[144:147], v[152:155], v[60:63]
	v_mfma_f32_16x16x32_bf16 v[52:55], v[136:139], v[160:163], v[52:55]
	v_mfma_f32_16x16x32_bf16 v[44:47], v[144:147], v[160:163], v[44:47]
	v_mfma_f32_16x16x32_bf16 v[36:39], v[136:139], v[168:171], v[36:39]
	v_mfma_f32_16x16x32_bf16 v[28:31], v[144:147], v[168:171], v[28:31]
	v_mfma_f32_16x16x32_bf16 v[20:23], v[136:139], v[176:179], v[20:23]
	v_mfma_f32_16x16x32_bf16 v[12:15], v[144:147], v[176:179], v[12:15]
	v_mfma_f32_16x16x32_bf16 v[56:59], v[180:183], v[148:151], v[56:59]
	v_mfma_f32_16x16x32_bf16 v[48:51], v[188:191], v[148:151], v[48:51]
	v_mfma_f32_16x16x32_bf16 v[40:43], v[180:183], v[156:159], v[40:43]
	v_mfma_f32_16x16x32_bf16 v[32:35], v[188:191], v[156:159], v[32:35]
	v_mfma_f32_16x16x32_bf16 v[24:27], v[180:183], v[164:167], v[24:27]
	v_mfma_f32_16x16x32_bf16 v[16:19], v[188:191], v[164:167], v[16:19]
	v_mfma_f32_16x16x32_bf16 v[8:11], v[180:183], v[172:175], v[8:11]
	v_mfma_f32_16x16x32_bf16 v[4:7], v[188:191], v[172:175], v[4:7]
	v_mfma_f32_16x16x32_bf16 v[56:59], v[184:187], v[152:155], v[56:59]
	v_mfma_f32_16x16x32_bf16 v[48:51], v[202:205], v[152:155], v[48:51]
	v_mfma_f32_16x16x32_bf16 v[40:43], v[184:187], v[160:163], v[40:43]
	v_mfma_f32_16x16x32_bf16 v[32:35], v[202:205], v[160:163], v[32:35]
	v_mfma_f32_16x16x32_bf16 v[24:27], v[184:187], v[168:171], v[24:27]
	v_mfma_f32_16x16x32_bf16 v[16:19], v[202:205], v[168:171], v[16:19]
	v_mfma_f32_16x16x32_bf16 v[8:11], v[184:187], v[176:179], v[8:11]
	v_mfma_f32_16x16x32_bf16 v[4:7], v[202:205], v[176:179], v[4:7]
	s_barrier
	s_setprio 0
	s_add_i32 s45, 0, 0x18000
	v_add_u32_e32 v144, s45, v1
	ds_read_b128 v[132:135], v144
	ds_read_b128 v[136:139], v144 offset:1024
	ds_read_b128 v[140:143], v144 offset:2048
	ds_read_b128 v[144:147], v144 offset:3072
	s_add_u32 s6, s20, 0x160000
	s_addc_u32 s7, s21, 0
	ds_read_b128 v[148:151], v224 offset:32768
	ds_read_b128 v[152:155], v224 offset:33792
	ds_read_b128 v[156:159], v224 offset:34816
	ds_read_b128 v[160:163], v224 offset:35840
	ds_read_b128 v[164:167], v224 offset:36864
	ds_read_b128 v[168:171], v224 offset:37888
	ds_read_b128 v[172:175], v224 offset:38912
	ds_read_b128 v[176:179], v224 offset:39936
	s_mov_b32 m0, s31
	s_nop 0
	global_load_lds_dwordx4 v196, s[6:7]
	s_mov_b32 m0, s35
	s_nop 0
	global_load_lds_dwordx4 v194, s[6:7]
	s_add_i32 s20, 0, 0x1c000
	v_add_u32_e32 v202, s20, v1
	ds_read_b128 v[180:183], v202
	ds_read_b128 v[184:187], v202 offset:1024
	ds_read_b128 v[188:191], v202 offset:2048
	ds_read_b128 v[202:205], v202 offset:3072
	s_waitcnt lgkmcnt(0)
	s_setprio 1
	s_barrier
	v_mfma_f32_16x16x32_bf16 v[128:131], v[132:135], v[148:151], v[128:131]
	v_mfma_f32_16x16x32_bf16 v[124:127], v[140:143], v[148:151], v[124:127]
	v_mfma_f32_16x16x32_bf16 v[112:115], v[132:135], v[156:159], v[112:115]
	v_mfma_f32_16x16x32_bf16 v[108:111], v[140:143], v[156:159], v[108:111]
	v_mfma_f32_16x16x32_bf16 v[100:103], v[132:135], v[164:167], v[100:103]
	v_mfma_f32_16x16x32_bf16 v[92:95], v[140:143], v[164:167], v[92:95]
	v_mfma_f32_16x16x32_bf16 v[84:87], v[132:135], v[172:175], v[84:87]
	v_mfma_f32_16x16x32_bf16 v[76:79], v[140:143], v[172:175], v[76:79]
	v_mfma_f32_16x16x32_bf16 v[128:131], v[136:139], v[152:155], v[128:131]
	v_mfma_f32_16x16x32_bf16 v[124:127], v[144:147], v[152:155], v[124:127]
	v_mfma_f32_16x16x32_bf16 v[112:115], v[136:139], v[160:163], v[112:115]
	v_mfma_f32_16x16x32_bf16 v[108:111], v[144:147], v[160:163], v[108:111]
	v_mfma_f32_16x16x32_bf16 v[100:103], v[136:139], v[168:171], v[100:103]
	v_mfma_f32_16x16x32_bf16 v[92:95], v[144:147], v[168:171], v[92:95]
	v_mfma_f32_16x16x32_bf16 v[84:87], v[136:139], v[176:179], v[84:87]
	v_mfma_f32_16x16x32_bf16 v[76:79], v[144:147], v[176:179], v[76:79]
	v_mfma_f32_16x16x32_bf16 v[120:123], v[180:183], v[148:151], v[120:123]
	v_mfma_f32_16x16x32_bf16 v[116:119], v[188:191], v[148:151], v[116:119]
	v_mfma_f32_16x16x32_bf16 v[104:107], v[180:183], v[156:159], v[104:107]
	v_mfma_f32_16x16x32_bf16 v[96:99], v[188:191], v[156:159], v[96:99]
	v_mfma_f32_16x16x32_bf16 v[88:91], v[180:183], v[164:167], v[88:91]
	v_mfma_f32_16x16x32_bf16 v[80:83], v[188:191], v[164:167], v[80:83]
	v_mfma_f32_16x16x32_bf16 v[72:75], v[180:183], v[172:175], v[72:75]
	v_mfma_f32_16x16x32_bf16 v[68:71], v[188:191], v[172:175], v[68:71]
	v_mfma_f32_16x16x32_bf16 v[120:123], v[184:187], v[152:155], v[120:123]
	v_mfma_f32_16x16x32_bf16 v[116:119], v[202:205], v[152:155], v[116:119]
	v_mfma_f32_16x16x32_bf16 v[104:107], v[184:187], v[160:163], v[104:107]
	v_mfma_f32_16x16x32_bf16 v[96:99], v[202:205], v[160:163], v[96:99]
	v_mfma_f32_16x16x32_bf16 v[88:91], v[184:187], v[168:171], v[88:91]
	v_mfma_f32_16x16x32_bf16 v[80:83], v[202:205], v[168:171], v[80:83]
	v_mfma_f32_16x16x32_bf16 v[72:75], v[184:187], v[176:179], v[72:75]
	v_mfma_f32_16x16x32_bf16 v[68:71], v[202:205], v[176:179], v[68:71]
	s_barrier
; __device__ __forceinline__ int opaque_tid() { int t = threadIdx.x; asm volatile("" : "+v"(t)); return t; }
; #define PG8_STAGE(bufoff, gbase, voff) do { _Pragma("unroll") for (int _i = 0; _i < 2; ++_i) \
;         __builtin_amdgcn_global_load_lds((const unsigned*)((const char*)(gbase) + (voff)[_i]), (LAS unsigned*)(lds + (bufoff) + ldsw + _i * 8192), 16, 0, 0); } while (0)
; #define PG8_MMA(ai, bj, At, Bt) do { __builtin_amdgcn_s_setprio(1); _Pragma("unroll") for (int m = 0; m < 4; ++m) _Pragma("unroll") for (int n = 0; n < 2; ++n) _Pragma("unroll") for (int k = 0; k < 2; ++k) \
;         acc[ai][bj][m][n] = __builtin_amdgcn_mfma_f32_16x16x32_bf16(Bt[n][k], At[m][k], acc[ai][bj][m][n], 0, 0, 0); __builtin_amdgcn_s_setprio(0); } while (0)
; #define PG8_WAIT_V(n) asm volatile("s_waitcnt vmcnt(" #n ")" ::: "memory")
; #define PG8_WAIT_L(n) asm volatile("s_waitcnt lgkmcnt(" #n ")" ::: "memory")
; #define PG8_BAR __builtin_amdgcn_s_barrier()
; #define PG8_SCHED __builtin_amdgcn_sched_barrier(0)
;     __device__ __forceinline__ void operator()(const f32x4 (&acc)[2][2][4][2], const Unit& u, int wr, int wc, int, int) const {
;         const int ol_ = opaque_tid() & 63, fr = ol_ & 15, fq = ol_ >> 4;
;         const int row0 = u.pm * BM + wr * 64 + fr, col0 = u.pn * BM + wc * 32 + 8 * fq;
;         u32x4 cin[2][4][2];
; #pragma unroll
;         for (int ai = 0; ai < 2; ++ai)
; #pragma unroll
;             for (int m = 0; m < 4; ++m)
; #pragma unroll
;                 for (int bj = 0; bj < 2; ++bj) cin[ai][m][bj] = *(const u32x4*)(C + (size_t)(row0 + ai * HALF + m * 16) * ldc + col0 + bj * HALF);
; template <class Epi, class Sched>
; __device__ __forceinline__ void gemm_phase(LAS unsigned char* lds, const Gemm g, const Sched& S, const Epi& E) {
;     ...
;             PG8_BAR; PG8_WAIT_L(0); PG8_MMA(1, 0, At, B0); PG8_BAR; PG8_SCHED;
;             PG8_STAGE(PG8_SB(1, 1), b3 + hstepB, voffB);
;             PG8_WAIT_V(6); PG8_BAR; PG8_MMA(1, 1, At, B1); PG8_BAR;
	s_setprio 0
	ds_read_b128 v[148:151], v224 offset:49152
	ds_read_b128 v[152:155], v224 offset:50176
	ds_read_b128 v[156:159], v224 offset:51200
	ds_read_b128 v[160:163], v224 offset:52224
	ds_read_b128 v[164:167], v224 offset:53248
	ds_read_b128 v[168:171], v224 offset:54272
	ds_read_b128 v[172:175], v224 offset:55296
	ds_read_b128 v[176:179], v224 offset:56320
	s_add_i32 s6, s45, s28
	v_lshl_add_u64 v[206:207], v[206:207], 0, s[8:9]
	s_mov_b32 m0, s6
	s_nop 0
	global_load_lds_dwordx4 v[206:207], off
	v_lshl_add_u64 v[206:207], v[208:209], 0, s[8:9]
	s_add_i32 m0, s6, 0x2000
	s_nop 0
	global_load_lds_dwordx4 v[206:207], off
	s_mov_b32 m0, s38
	v_lshl_add_u64 v[206:207], v[210:211], 0, s[8:9]
	global_load_lds_dwordx4 v[206:207], off
	v_lshl_add_u64 v[206:207], v[212:213], 0, s[8:9]
	s_mov_b32 m0, s39
	s_nop 0
	global_load_lds_dwordx4 v[206:207], off
	s_add_u32 s6, s18, 0x160080
	s_addc_u32 s7, s19, 0
	s_add_i32 s18, s20, s28
	s_mov_b32 m0, s18
	s_nop 0
	global_load_lds_dwordx4 v2, s[6:7]
	s_add_i32 m0, s18, 0x2000
	s_nop 0
	global_load_lds_dwordx4 v192, s[6:7]
	s_add_i32 s44, s44, 2
	s_add_u32 s42, s42, 0x100
	s_addc_u32 s43, s43, 0
	s_cmpk_gt_u32 s44, 0x55
	s_mov_b64 s[6:7], s[14:15]
	s_waitcnt lgkmcnt(0)
	s_waitcnt vmcnt(6)
	s_setprio 1
	s_barrier
	v_mfma_f32_16x16x32_bf16 v[64:67], v[132:135], v[148:151], v[64:67]
	v_mfma_f32_16x16x32_bf16 v[60:63], v[140:143], v[148:151], v[60:63]
	v_mfma_f32_16x16x32_bf16 v[52:55], v[132:135], v[156:159], v[52:55]
	v_mfma_f32_16x16x32_bf16 v[44:47], v[140:143], v[156:159], v[44:47]
	v_mfma_f32_16x16x32_bf16 v[36:39], v[132:135], v[164:167], v[36:39]
	v_mfma_f32_16x16x32_bf16 v[28:31], v[140:143], v[164:167], v[28:31]
	v_mfma_f32_16x16x32_bf16 v[20:23], v[132:135], v[172:175], v[20:23]
	v_mfma_f32_16x16x32_bf16 v[12:15], v[140:143], v[172:175], v[12:15]
	v_mfma_f32_16x16x32_bf16 v[64:67], v[136:139], v[152:155], v[64:67]
	v_mfma_f32_16x16x32_bf16 v[60:63], v[144:147], v[152:155], v[60:63]
	v_mfma_f32_16x16x32_bf16 v[52:55], v[136:139], v[160:163], v[52:55]
	v_mfma_f32_16x16x32_bf16 v[44:47], v[144:147], v[160:163], v[44:47]
	v_mfma_f32_16x16x32_bf16 v[36:39], v[136:139], v[168:171], v[36:39]
	v_mfma_f32_16x16x32_bf16 v[28:31], v[144:147], v[168:171], v[28:31]
	v_mfma_f32_16x16x32_bf16 v[20:23], v[136:139], v[176:179], v[20:23]
	v_mfma_f32_16x16x32_bf16 v[12:15], v[144:147], v[176:179], v[12:15]
	v_mfma_f32_16x16x32_bf16 v[56:59], v[180:183], v[148:151], v[56:59]
	v_mfma_f32_16x16x32_bf16 v[48:51], v[188:191], v[148:151], v[48:51]
	v_mfma_f32_16x16x32_bf16 v[40:43], v[180:183], v[156:159], v[40:43]
	v_mfma_f32_16x16x32_bf16 v[32:35], v[188:191], v[156:159], v[32:35]
	v_mfma_f32_16x16x32_bf16 v[24:27], v[180:183], v[164:167], v[24:27]
	v_mfma_f32_16x16x32_bf16 v[16:19], v[188:191], v[164:167], v[16:19]
	v_mfma_f32_16x16x32_bf16 v[8:11], v[180:183], v[172:175], v[8:11]
	v_mfma_f32_16x16x32_bf16 v[4:7], v[188:191], v[172:175], v[4:7]
	v_mfma_f32_16x16x32_bf16 v[56:59], v[184:187], v[152:155], v[56:59]
	v_mfma_f32_16x16x32_bf16 v[48:51], v[202:205], v[152:155], v[48:51]
	v_mfma_f32_16x16x32_bf16 v[40:43], v[184:187], v[160:163], v[40:43]
	v_mfma_f32_16x16x32_bf16 v[32:35], v[202:205], v[160:163], v[32:35]
	v_mfma_f32_16x16x32_bf16 v[24:27], v[184:187], v[168:171], v[24:27]
	v_mfma_f32_16x16x32_bf16 v[16:19], v[202:205], v[168:171], v[16:19]
	v_mfma_f32_16x16x32_bf16 v[8:11], v[184:187], v[176:179], v[8:11]
	v_mfma_f32_16x16x32_bf16 v[4:7], v[202:205], v[176:179], v[4:7]
	s_barrier
	s_cbranch_scc0 .LBB0_1666
	s_setprio 0
	v_mov_b32_e32 v133, v0
	s_lshl_b32 s6, s50, 8
	s_add_i32 s6, s6, s36
	v_and_or_b32 v132, v133, 15, s6
	s_lshl_b32 s6, s49, 8
	v_lshrrev_b32_e32 v133, 1, v133
	v_and_or_b32 v133, v133, 24, s6
	v_or_b32_e32 v134, s37, v133
	v_ashrrev_i32_e32 v135, 31, v134
	v_lshlrev_b64 v[202:203], 1, v[134:135]
	v_ashrrev_i32_e32 v133, 31, v132
	v_lshl_add_u64 v[134:135], s[88:89], 0, v[202:203]
	v_lshlrev_b64 v[226:227], 12, v[132:133]
	v_lshl_add_u64 v[136:137], v[134:135], 0, v[226:227]
	global_load_dwordx4 v[216:219], v[136:137], off
	global_load_dwordx4 v[188:191], v[136:137], off offset:256
	v_or_b32_e32 v136, 16, v132
	v_ashrrev_i32_e32 v137, 31, v136
	v_lshlrev_b64 v[222:223], 12, v[136:137]
	v_lshl_add_u64 v[136:137], v[134:135], 0, v[222:223]
	global_load_dwordx4 v[184:187], v[136:137], off
	global_load_dwordx4 v[180:183], v[136:137], off offset:256
	v_or_b32_e32 v136, 32, v132
	v_ashrrev_i32_e32 v137, 31, v136
	v_lshlrev_b64 v[220:221], 12, v[136:137]
	v_lshl_add_u64 v[136:137], v[134:135], 0, v[220:221]
	global_load_dwordx4 v[176:179], v[136:137], off
	global_load_dwordx4 v[168:171], v[136:137], off offset:256
	v_or_b32_e32 v132, 48, v132
	v_ashrrev_i32_e32 v133, 31, v132
	v_lshlrev_b64 v[212:213], 12, v[132:133]
	v_lshl_add_u64 v[132:133], v[134:135], 0, v[212:213]
	global_load_dwordx4 v[172:175], v[132:133], off
	global_load_dwordx4 v[164:167], v[132:133], off offset:256
	s_mov_b64 s[6:7], 0x80000
	v_lshl_add_u64 v[210:211], v[226:227], 0, s[6:7]
	v_lshl_add_u64 v[132:133], v[134:135], 0, v[210:211]
	global_load_dwordx4 v[160:163], v[132:133], off
	global_load_dwordx4 v[156:159], v[132:133], off offset:256
	s_mov_b64 s[6:7], 0x90000
	v_lshl_add_u64 v[208:209], v[226:227], 0, s[6:7]
	v_lshl_add_u64 v[132:133], v[134:135], 0, v[208:209]
	global_load_dwordx4 v[152:155], v[132:133], off
	global_load_dwordx4 v[148:151], v[132:133], off offset:256
	s_mov_b64 s[6:7], 0xa0000
	v_lshl_add_u64 v[206:207], v[226:227], 0, s[6:7]
	v_lshl_add_u64 v[132:133], v[134:135], 0, v[206:207]
	global_load_dwordx4 v[144:147], v[132:133], off
	global_load_dwordx4 v[140:143], v[132:133], off offset:256
	s_mov_b64 s[6:7], 0xb0000
	v_lshl_add_u64 v[204:205], v[226:227], 0, s[6:7]
	v_lshl_add_u64 v[132:133], v[134:135], 0, v[204:205]
	global_load_dwordx4 v[136:139], v[132:133], off
	s_nop 0
	global_load_dwordx4 v[132:135], v[132:133], off offset:256
	s_and_b64 vcc, exec, s[40:41]
	s_mov_b32 s49, s47
	s_mov_b32 s50, s48
	s_mov_b64 s[14:15], s[4:5]
	s_mov_b64 s[6:7], s[0:1]
	s_waitcnt vmcnt(15)
; __device__ __forceinline__ unsigned cvt_pk_bf16(float lo, float hi) { const f32x2 v = {lo, hi}; const bf16v2_ r = __builtin_convertvector(v, bf16v2_); return __builtin_bit_cast(unsigned, r); }
; __device__ __forceinline__ float bflo(unsigned w) { return __uint_as_float(w << 16); }
; __device__ __forceinline__ float bfhi(unsigned w) { return __uint_as_float(w & 0xffff0000u); }
;     __device__ __forceinline__ void operator()(const f32x4 (&acc)[2][2][4][2], const Unit& u, int wr, int wc, int, int) const {
;     ...
;                 for (int bj = 0; bj < 2; ++bj) { const u32x4 c = cin[ai][m][bj]; const f32x4 v0 = acc[ai][bj][m][0], v1 = acc[ai][bj][m][1];
;                     u32x4 w; w.x = cvt_pk_bf16(bflo(c.x) + v0[0], bfhi(c.x) + v0[1]); w.y = cvt_pk_bf16(bflo(c.y) + v0[2], bfhi(c.y) + v0[3]);
;                     w.z = cvt_pk_bf16(bflo(c.z) + v1[0], bfhi(c.z) + v1[1]); w.w = cvt_pk_bf16(bflo(c.w) + v1[2], bfhi(c.w) + v1[3]);
;                     *(u32x4*)(C + (size_t)(row0 + ai * HALF + m * 16) * ldc + col0 + bj * HALF) = w; }
	v_lshlrev_b32_e32 v228, 16, v216
	v_and_b32_e32 v229, 0xffff0000, v216
	v_lshlrev_b32_e32 v216, 16, v217
	v_and_b32_e32 v217, 0xffff0000, v217
	v_pk_add_f32 v[128:129], v[128:129], v[228:229]
	v_pk_add_f32 v[130:131], v[130:131], v[216:217]
	v_cvt_pk_bf16_f32 v128, v128, v129
	v_cvt_pk_bf16_f32 v129, v130, v131
	v_lshlrev_b32_e32 v130, 16, v218
	v_and_b32_e32 v131, 0xffff0000, v218
	v_pk_add_f32 v[124:125], v[124:125], v[130:131]
	s_nop 0
	v_cvt_pk_bf16_f32 v130, v124, v125
	v_lshlrev_b32_e32 v124, 16, v219
	v_and_b32_e32 v125, 0xffff0000, v219
	v_pk_add_f32 v[124:125], v[126:127], v[124:125]
	s_waitcnt vmcnt(14)
	v_lshlrev_b32_e32 v126, 16, v188
	v_and_b32_e32 v127, 0xffff0000, v188
	v_pk_add_f32 v[120:121], v[120:121], v[126:127]
	v_lshlrev_b32_e32 v126, 16, v189
	v_and_b32_e32 v127, 0xffff0000, v189
	v_pk_add_f32 v[122:123], v[122:123], v[126:127]
	v_cvt_pk_bf16_f32 v120, v120, v121
	v_cvt_pk_bf16_f32 v121, v122, v123
	v_lshlrev_b32_e32 v122, 16, v190
	v_and_b32_e32 v123, 0xffff0000, v190
	v_pk_add_f32 v[116:117], v[116:117], v[122:123]
	v_cvt_pk_bf16_f32 v131, v124, v125
	v_cvt_pk_bf16_f32 v122, v116, v117
	v_lshlrev_b32_e32 v116, 16, v191
	v_and_b32_e32 v117, 0xffff0000, v191
	v_pk_add_f32 v[116:117], v[118:119], v[116:117]
	v_lshl_add_u64 v[124:125], s[88:89], 0, v[226:227]
	v_cvt_pk_bf16_f32 v123, v116, v117
	s_waitcnt vmcnt(13)
	v_lshlrev_b32_e32 v116, 16, v184
	v_and_b32_e32 v117, 0xffff0000, v184
	v_pk_add_f32 v[112:113], v[112:113], v[116:117]
	v_lshlrev_b32_e32 v116, 16, v185
	v_and_b32_e32 v117, 0xffff0000, v185
	v_pk_add_f32 v[114:115], v[114:115], v[116:117]
	v_cvt_pk_bf16_f32 v112, v112, v113
	v_cvt_pk_bf16_f32 v113, v114, v115
	v_lshlrev_b32_e32 v114, 16, v186
	v_and_b32_e32 v115, 0xffff0000, v186
	v_pk_add_f32 v[108:109], v[108:109], v[114:115]
	v_lshl_add_u64 v[124:125], v[124:125], 0, v[202:203]
	v_cvt_pk_bf16_f32 v114, v108, v109
	v_lshlrev_b32_e32 v108, 16, v187
	v_and_b32_e32 v109, 0xffff0000, v187
	v_pk_add_f32 v[108:109], v[110:111], v[108:109]
	s_waitcnt vmcnt(12)
	v_lshlrev_b32_e32 v110, 16, v180
	v_and_b32_e32 v111, 0xffff0000, v180
	v_pk_add_f32 v[104:105], v[104:105], v[110:111]
	v_lshlrev_b32_e32 v110, 16, v181
	v_and_b32_e32 v111, 0xffff0000, v181
	v_pk_add_f32 v[106:107], v[106:107], v[110:111]
	v_cvt_pk_bf16_f32 v104, v104, v105
	v_cvt_pk_bf16_f32 v105, v106, v107
	v_lshlrev_b32_e32 v106, 16, v182
	v_and_b32_e32 v107, 0xffff0000, v182
	v_pk_add_f32 v[96:97], v[96:97], v[106:107]
	v_cvt_pk_bf16_f32 v115, v108, v109
	v_cvt_pk_bf16_f32 v106, v96, v97
	v_lshlrev_b32_e32 v96, 16, v183
	v_and_b32_e32 v97, 0xffff0000, v183
	v_pk_add_f32 v[96:97], v[98:99], v[96:97]
	s_waitcnt vmcnt(11)
	v_lshlrev_b32_e32 v98, 16, v177
	v_cvt_pk_bf16_f32 v107, v96, v97
	v_lshlrev_b32_e32 v96, 16, v176
	v_and_b32_e32 v97, 0xffff0000, v176
	v_and_b32_e32 v99, 0xffff0000, v177
	v_pk_add_f32 v[96:97], v[100:101], v[96:97]
	v_pk_add_f32 v[98:99], v[102:103], v[98:99]
	v_cvt_pk_bf16_f32 v96, v96, v97
	v_cvt_pk_bf16_f32 v97, v98, v99
	v_lshlrev_b32_e32 v98, 16, v178
	v_and_b32_e32 v99, 0xffff0000, v178
	v_pk_add_f32 v[92:93], v[92:93], v[98:99]
	v_lshl_add_u64 v[108:109], s[88:89], 0, v[222:223]
	v_cvt_pk_bf16_f32 v98, v92, v93
	v_lshlrev_b32_e32 v92, 16, v179
	v_and_b32_e32 v93, 0xffff0000, v179
	v_pk_add_f32 v[92:93], v[94:95], v[92:93]
	s_waitcnt vmcnt(10)
	v_lshlrev_b32_e32 v94, 16, v168
	v_and_b32_e32 v95, 0xffff0000, v168
	v_pk_add_f32 v[88:89], v[88:89], v[94:95]
	v_lshlrev_b32_e32 v94, 16, v169
	v_and_b32_e32 v95, 0xffff0000, v169
	v_pk_add_f32 v[90:91], v[90:91], v[94:95]
	v_cvt_pk_bf16_f32 v88, v88, v89
	v_cvt_pk_bf16_f32 v89, v90, v91
	v_lshlrev_b32_e32 v90, 16, v170
	v_and_b32_e32 v91, 0xffff0000, v170
	v_pk_add_f32 v[80:81], v[80:81], v[90:91]
	v_cvt_pk_bf16_f32 v99, v92, v93
	v_cvt_pk_bf16_f32 v90, v80, v81
	v_lshlrev_b32_e32 v80, 16, v171
	v_and_b32_e32 v81, 0xffff0000, v171
	v_pk_add_f32 v[80:81], v[82:83], v[80:81]
	s_waitcnt vmcnt(9)
	v_lshlrev_b32_e32 v82, 16, v173
	v_cvt_pk_bf16_f32 v91, v80, v81
	v_lshlrev_b32_e32 v80, 16, v172
	v_and_b32_e32 v81, 0xffff0000, v172
	v_and_b32_e32 v83, 0xffff0000, v173
	v_pk_add_f32 v[80:81], v[84:85], v[80:81]
	v_pk_add_f32 v[82:83], v[86:87], v[82:83]
	v_cvt_pk_bf16_f32 v80, v80, v81
	v_cvt_pk_bf16_f32 v81, v82, v83
	v_lshlrev_b32_e32 v82, 16, v174
	v_and_b32_e32 v83, 0xffff0000, v174
	v_pk_add_f32 v[76:77], v[76:77], v[82:83]
	v_lshl_add_u64 v[92:93], s[88:89], 0, v[220:221]
	v_cvt_pk_bf16_f32 v82, v76, v77
	v_lshlrev_b32_e32 v76, 16, v175
	v_and_b32_e32 v77, 0xffff0000, v175
	v_pk_add_f32 v[76:77], v[78:79], v[76:77]
	s_waitcnt vmcnt(8)
	v_lshlrev_b32_e32 v78, 16, v164
	v_and_b32_e32 v79, 0xffff0000, v164
	v_pk_add_f32 v[72:73], v[72:73], v[78:79]
	v_lshlrev_b32_e32 v78, 16, v165
	v_and_b32_e32 v79, 0xffff0000, v165
	v_pk_add_f32 v[74:75], v[74:75], v[78:79]
	v_cvt_pk_bf16_f32 v72, v72, v73
	v_cvt_pk_bf16_f32 v73, v74, v75
	v_lshlrev_b32_e32 v74, 16, v166
	v_and_b32_e32 v75, 0xffff0000, v166
	v_pk_add_f32 v[68:69], v[68:69], v[74:75]
	v_cvt_pk_bf16_f32 v83, v76, v77
	v_cvt_pk_bf16_f32 v74, v68, v69
	v_lshlrev_b32_e32 v68, 16, v167
	v_and_b32_e32 v69, 0xffff0000, v167
	v_pk_add_f32 v[68:69], v[70:71], v[68:69]
	v_lshl_add_u64 v[76:77], s[88:89], 0, v[212:213]
	v_cvt_pk_bf16_f32 v75, v68, v69
	s_waitcnt vmcnt(7)
	v_lshlrev_b32_e32 v68, 16, v160
	v_and_b32_e32 v69, 0xffff0000, v160
	v_pk_add_f32 v[64:65], v[64:65], v[68:69]
	v_lshlrev_b32_e32 v68, 16, v161
	v_and_b32_e32 v69, 0xffff0000, v161
	v_pk_add_f32 v[66:67], v[66:67], v[68:69]
	v_cvt_pk_bf16_f32 v64, v64, v65
	v_cvt_pk_bf16_f32 v65, v66, v67
	v_lshlrev_b32_e32 v66, 16, v162
	v_and_b32_e32 v67, 0xffff0000, v162
	v_pk_add_f32 v[60:61], v[60:61], v[66:67]
	v_lshl_add_u64 v[108:109], v[108:109], 0, v[202:203]
	v_cvt_pk_bf16_f32 v66, v60, v61
	v_lshlrev_b32_e32 v60, 16, v163
	v_and_b32_e32 v61, 0xffff0000, v163
	v_pk_add_f32 v[60:61], v[62:63], v[60:61]
	s_waitcnt vmcnt(6)
; __device__ __forceinline__ unsigned cvt_pk_bf16(float lo, float hi) { const f32x2 v = {lo, hi}; const bf16v2_ r = __builtin_convertvector(v, bf16v2_); return __builtin_bit_cast(unsigned, r); }
; __device__ __forceinline__ float bflo(unsigned w) { return __uint_as_float(w << 16); }
; __device__ __forceinline__ float bfhi(unsigned w) { return __uint_as_float(w & 0xffff0000u); }
;     __device__ __forceinline__ void operator()(const f32x4 (&acc)[2][2][4][2], const Unit& u, int wr, int wc, int, int) const {
;     ...
;                 for (int bj = 0; bj < 2; ++bj) { const u32x4 c = cin[ai][m][bj]; const f32x4 v0 = acc[ai][bj][m][0], v1 = acc[ai][bj][m][1];
;                     u32x4 w; w.x = cvt_pk_bf16(bflo(c.x) + v0[0], bfhi(c.x) + v0[1]); w.y = cvt_pk_bf16(bflo(c.y) + v0[2], bfhi(c.y) + v0[3]);
;                     w.z = cvt_pk_bf16(bflo(c.z) + v1[0], bfhi(c.z) + v1[1]); w.w = cvt_pk_bf16(bflo(c.w) + v1[2], bfhi(c.w) + v1[3]);
;                     *(u32x4*)(C + (size_t)(row0 + ai * HALF + m * 16) * ldc + col0 + bj * HALF) = w; }
	v_lshlrev_b32_e32 v62, 16, v156
	v_and_b32_e32 v63, 0xffff0000, v156
	v_pk_add_f32 v[56:57], v[56:57], v[62:63]
	v_lshlrev_b32_e32 v62, 16, v157
	v_and_b32_e32 v63, 0xffff0000, v157
	v_pk_add_f32 v[58:59], v[58:59], v[62:63]
	v_cvt_pk_bf16_f32 v56, v56, v57
	v_cvt_pk_bf16_f32 v57, v58, v59
	v_lshlrev_b32_e32 v58, 16, v158
	v_and_b32_e32 v59, 0xffff0000, v158
	v_pk_add_f32 v[48:49], v[48:49], v[58:59]
	v_cvt_pk_bf16_f32 v67, v60, v61
	v_cvt_pk_bf16_f32 v58, v48, v49
	v_lshlrev_b32_e32 v48, 16, v159
	v_and_b32_e32 v49, 0xffff0000, v159
	v_pk_add_f32 v[48:49], v[50:51], v[48:49]
	s_waitcnt vmcnt(5)
	v_lshlrev_b32_e32 v50, 16, v153
	v_cvt_pk_bf16_f32 v59, v48, v49
	v_lshlrev_b32_e32 v48, 16, v152
	v_and_b32_e32 v49, 0xffff0000, v152
	v_and_b32_e32 v51, 0xffff0000, v153
	v_pk_add_f32 v[48:49], v[52:53], v[48:49]
	v_pk_add_f32 v[50:51], v[54:55], v[50:51]
	v_cvt_pk_bf16_f32 v48, v48, v49
	v_cvt_pk_bf16_f32 v49, v50, v51
	v_lshlrev_b32_e32 v50, 16, v154
	v_and_b32_e32 v51, 0xffff0000, v154
	v_pk_add_f32 v[44:45], v[44:45], v[50:51]
	v_lshl_add_u64 v[60:61], s[88:89], 0, v[210:211]
	v_cvt_pk_bf16_f32 v50, v44, v45
	v_lshlrev_b32_e32 v44, 16, v155
	v_and_b32_e32 v45, 0xffff0000, v155
	v_pk_add_f32 v[44:45], v[46:47], v[44:45]
	s_waitcnt vmcnt(4)
	v_lshlrev_b32_e32 v46, 16, v148
	v_and_b32_e32 v47, 0xffff0000, v148
	v_pk_add_f32 v[40:41], v[40:41], v[46:47]
	v_lshlrev_b32_e32 v46, 16, v149
	v_and_b32_e32 v47, 0xffff0000, v149
	v_pk_add_f32 v[42:43], v[42:43], v[46:47]
	v_cvt_pk_bf16_f32 v40, v40, v41
	v_cvt_pk_bf16_f32 v41, v42, v43
	v_lshlrev_b32_e32 v42, 16, v150
	v_and_b32_e32 v43, 0xffff0000, v150
	v_pk_add_f32 v[32:33], v[32:33], v[42:43]
	v_cvt_pk_bf16_f32 v51, v44, v45
	v_cvt_pk_bf16_f32 v42, v32, v33
	v_lshlrev_b32_e32 v32, 16, v151
	v_and_b32_e32 v33, 0xffff0000, v151
	v_pk_add_f32 v[32:33], v[34:35], v[32:33]
	s_waitcnt vmcnt(3)
	v_lshlrev_b32_e32 v34, 16, v145
	v_cvt_pk_bf16_f32 v43, v32, v33
	v_lshlrev_b32_e32 v32, 16, v144
	v_and_b32_e32 v33, 0xffff0000, v144
	v_and_b32_e32 v35, 0xffff0000, v145
	v_pk_add_f32 v[32:33], v[36:37], v[32:33]
	v_pk_add_f32 v[34:35], v[38:39], v[34:35]
	v_cvt_pk_bf16_f32 v32, v32, v33
	v_cvt_pk_bf16_f32 v33, v34, v35
	v_lshlrev_b32_e32 v34, 16, v146
	v_and_b32_e32 v35, 0xffff0000, v146
	v_pk_add_f32 v[28:29], v[28:29], v[34:35]
	v_lshl_add_u64 v[44:45], s[88:89], 0, v[208:209]
	v_cvt_pk_bf16_f32 v34, v28, v29
	v_lshlrev_b32_e32 v28, 16, v147
	v_and_b32_e32 v29, 0xffff0000, v147
	v_pk_add_f32 v[28:29], v[30:31], v[28:29]
	s_waitcnt vmcnt(2)
	v_lshlrev_b32_e32 v30, 16, v140
	v_and_b32_e32 v31, 0xffff0000, v140
	v_pk_add_f32 v[24:25], v[24:25], v[30:31]
	v_lshlrev_b32_e32 v30, 16, v141
	v_and_b32_e32 v31, 0xffff0000, v141
	v_pk_add_f32 v[26:27], v[26:27], v[30:31]
	v_cvt_pk_bf16_f32 v24, v24, v25
	v_cvt_pk_bf16_f32 v25, v26, v27
	v_lshlrev_b32_e32 v26, 16, v142
	v_and_b32_e32 v27, 0xffff0000, v142
	v_pk_add_f32 v[16:17], v[16:17], v[26:27]
	v_cvt_pk_bf16_f32 v35, v28, v29
	v_cvt_pk_bf16_f32 v26, v16, v17
	v_lshlrev_b32_e32 v16, 16, v143
	v_and_b32_e32 v17, 0xffff0000, v143
	v_pk_add_f32 v[16:17], v[18:19], v[16:17]
	s_waitcnt vmcnt(1)
	v_lshlrev_b32_e32 v18, 16, v137
	v_cvt_pk_bf16_f32 v27, v16, v17
	v_lshlrev_b32_e32 v16, 16, v136
	v_and_b32_e32 v17, 0xffff0000, v136
	v_and_b32_e32 v19, 0xffff0000, v137
	v_pk_add_f32 v[16:17], v[20:21], v[16:17]
	v_pk_add_f32 v[18:19], v[22:23], v[18:19]
	v_cvt_pk_bf16_f32 v16, v16, v17
	v_cvt_pk_bf16_f32 v17, v18, v19
	v_lshlrev_b32_e32 v18, 16, v138
	v_and_b32_e32 v19, 0xffff0000, v138
	v_pk_add_f32 v[12:13], v[12:13], v[18:19]
	v_lshl_add_u64 v[28:29], s[88:89], 0, v[206:207]
	v_cvt_pk_bf16_f32 v18, v12, v13
	v_lshlrev_b32_e32 v12, 16, v139
	v_and_b32_e32 v13, 0xffff0000, v139
	v_pk_add_f32 v[12:13], v[14:15], v[12:13]
	s_waitcnt vmcnt(0)
; __device__ __forceinline__ unsigned cvt_pk_bf16(float lo, float hi) { const f32x2 v = {lo, hi}; const bf16v2_ r = __builtin_convertvector(v, bf16v2_); return __builtin_bit_cast(unsigned, r); }
; __device__ __forceinline__ float bflo(unsigned w) { return __uint_as_float(w << 16); }
; __device__ __forceinline__ float bfhi(unsigned w) { return __uint_as_float(w & 0xffff0000u); }
;     __device__ __forceinline__ void operator()(const f32x4 (&acc)[2][2][4][2], const Unit& u, int wr, int wc, int, int) const {
;     ...
;                 for (int bj = 0; bj < 2; ++bj) cin[ai][m][bj] = *(const u32x4*)(C + (size_t)(row0 + ai * HALF + m * 16) * ldc + col0 + bj * HALF);
; #pragma unroll
;         for (int ai = 0; ai < 2; ++ai)
; #pragma unroll
;             for (int m = 0; m < 4; ++m)
; #pragma unroll
;                 for (int bj = 0; bj < 2; ++bj) { const u32x4 c = cin[ai][m][bj]; const f32x4 v0 = acc[ai][bj][m][0], v1 = acc[ai][bj][m][1];
;                     u32x4 w; w.x = cvt_pk_bf16(bflo(c.x) + v0[0], bfhi(c.x) + v0[1]); w.y = cvt_pk_bf16(bflo(c.y) + v0[2], bfhi(c.y) + v0[3]);
;                     w.z = cvt_pk_bf16(bflo(c.z) + v1[0], bfhi(c.z) + v1[1]); w.w = cvt_pk_bf16(bflo(c.w) + v1[2], bfhi(c.w) + v1[3]);
;                     *(u32x4*)(C + (size_t)(row0 + ai * HALF + m * 16) * ldc + col0 + bj * HALF) = w; }
	v_lshlrev_b32_e32 v14, 16, v132
	v_and_b32_e32 v15, 0xffff0000, v132
	v_pk_add_f32 v[8:9], v[8:9], v[14:15]
	v_lshlrev_b32_e32 v14, 16, v133
	v_and_b32_e32 v15, 0xffff0000, v133
	v_pk_add_f32 v[10:11], v[10:11], v[14:15]
	v_cvt_pk_bf16_f32 v8, v8, v9
	v_cvt_pk_bf16_f32 v9, v10, v11
	v_lshlrev_b32_e32 v10, 16, v134
	v_and_b32_e32 v11, 0xffff0000, v134
	v_pk_add_f32 v[4:5], v[4:5], v[10:11]
	v_cvt_pk_bf16_f32 v19, v12, v13
	v_cvt_pk_bf16_f32 v10, v4, v5
	v_lshlrev_b32_e32 v4, 16, v135
	v_and_b32_e32 v5, 0xffff0000, v135
	v_lshl_add_u64 v[12:13], s[88:89], 0, v[204:205]
	v_pk_add_f32 v[4:5], v[6:7], v[4:5]
	v_lshl_add_u64 v[92:93], v[92:93], 0, v[202:203]
	v_lshl_add_u64 v[76:77], v[76:77], 0, v[202:203]
	v_lshl_add_u64 v[60:61], v[60:61], 0, v[202:203]
	v_lshl_add_u64 v[44:45], v[44:45], 0, v[202:203]
	v_lshl_add_u64 v[28:29], v[28:29], 0, v[202:203]
	v_lshl_add_u64 v[12:13], v[12:13], 0, v[202:203]
	v_cvt_pk_bf16_f32 v11, v4, v5
	global_store_dwordx4 v[124:125], v[128:131], off
	global_store_dwordx4 v[124:125], v[120:123], off offset:256
	global_store_dwordx4 v[108:109], v[112:115], off
	global_store_dwordx4 v[108:109], v[104:107], off offset:256
	global_store_dwordx4 v[92:93], v[96:99], off
	global_store_dwordx4 v[92:93], v[88:91], off offset:256
	global_store_dwordx4 v[76:77], v[80:83], off
	global_store_dwordx4 v[76:77], v[72:75], off offset:256
	global_store_dwordx4 v[60:61], v[64:67], off
	global_store_dwordx4 v[60:61], v[56:59], off offset:256
	global_store_dwordx4 v[44:45], v[48:51], off
	global_store_dwordx4 v[44:45], v[40:43], off offset:256
	global_store_dwordx4 v[28:29], v[32:35], off
	global_store_dwordx4 v[28:29], v[24:27], off offset:256
	global_store_dwordx4 v[12:13], v[16:19], off
	global_store_dwordx4 v[12:13], v[8:11], off offset:256
	v_subrev_u32_e32 v216, s88, v124
	v_bfe_u32 v217, v216, 4, 8
	v_lshrrev_b32_e32 v216, 12, v216
	v_and_b32_e32 v218, 15, v217
	v_lshrrev_b32_e32 v217, 5, v217
	v_lshl_or_b32 v217, v217, 4, v218
	v_lshlrev_b32_e32 v217, 17, v217
	v_lshl_add_u32 v216, v216, 2, v217
	v_add_u32_e32 v216, 0x1e000000, v216
	v_mov_b32_e32 v188, 0
	v_dot2c_f32_bf16_e32 v188, v128, v128
	v_dot2c_f32_bf16_e32 v188, v129, v129
	v_dot2c_f32_bf16_e32 v188, v130, v130
	v_dot2c_f32_bf16_e32 v188, v131, v131
	v_dot2c_f32_bf16_e32 v188, v120, v120
	v_dot2c_f32_bf16_e32 v188, v121, v121
	v_dot2c_f32_bf16_e32 v188, v122, v122
	v_dot2c_f32_bf16_e32 v188, v123, v123
	s_nop 2
	global_store_dword v216, v188, s[88:89]
	v_mov_b32_e32 v189, 0
	v_dot2c_f32_bf16_e32 v189, v112, v112
	v_dot2c_f32_bf16_e32 v189, v113, v113
	v_dot2c_f32_bf16_e32 v189, v114, v114
	v_dot2c_f32_bf16_e32 v189, v115, v115
	v_dot2c_f32_bf16_e32 v189, v104, v104
	v_dot2c_f32_bf16_e32 v189, v105, v105
	v_dot2c_f32_bf16_e32 v189, v106, v106
	v_dot2c_f32_bf16_e32 v189, v107, v107
	s_nop 2
	global_store_dword v216, v189, s[88:89] offset:64
	v_mov_b32_e32 v188, 0
	v_dot2c_f32_bf16_e32 v188, v96, v96
	v_dot2c_f32_bf16_e32 v188, v97, v97
	v_dot2c_f32_bf16_e32 v188, v98, v98
	v_dot2c_f32_bf16_e32 v188, v99, v99
	v_dot2c_f32_bf16_e32 v188, v88, v88
	v_dot2c_f32_bf16_e32 v188, v89, v89
	v_dot2c_f32_bf16_e32 v188, v90, v90
	v_dot2c_f32_bf16_e32 v188, v91, v91
	s_nop 2
	global_store_dword v216, v188, s[88:89] offset:128
	v_mov_b32_e32 v189, 0
	v_dot2c_f32_bf16_e32 v189, v80, v80
	v_dot2c_f32_bf16_e32 v189, v81, v81
	v_dot2c_f32_bf16_e32 v189, v82, v82
	v_dot2c_f32_bf16_e32 v189, v83, v83
	v_dot2c_f32_bf16_e32 v189, v72, v72
	v_dot2c_f32_bf16_e32 v189, v73, v73
	v_dot2c_f32_bf16_e32 v189, v74, v74
	v_dot2c_f32_bf16_e32 v189, v75, v75
	s_nop 2
	global_store_dword v216, v189, s[88:89] offset:192
	v_mov_b32_e32 v188, 0
	v_dot2c_f32_bf16_e32 v188, v64, v64
	v_dot2c_f32_bf16_e32 v188, v65, v65
	v_dot2c_f32_bf16_e32 v188, v66, v66
	v_dot2c_f32_bf16_e32 v188, v67, v67
	v_dot2c_f32_bf16_e32 v188, v56, v56
	v_dot2c_f32_bf16_e32 v188, v57, v57
	v_dot2c_f32_bf16_e32 v188, v58, v58
	v_dot2c_f32_bf16_e32 v188, v59, v59
	s_nop 2
	global_store_dword v216, v188, s[88:89] offset:512
	v_mov_b32_e32 v189, 0
	v_dot2c_f32_bf16_e32 v189, v48, v48
	v_dot2c_f32_bf16_e32 v189, v49, v49
	v_dot2c_f32_bf16_e32 v189, v50, v50
	v_dot2c_f32_bf16_e32 v189, v51, v51
	v_dot2c_f32_bf16_e32 v189, v40, v40
	v_dot2c_f32_bf16_e32 v189, v41, v41
	v_dot2c_f32_bf16_e32 v189, v42, v42
	v_dot2c_f32_bf16_e32 v189, v43, v43
	s_nop 2
	global_store_dword v216, v189, s[88:89] offset:576
	v_mov_b32_e32 v188, 0
	v_dot2c_f32_bf16_e32 v188, v32, v32
	v_dot2c_f32_bf16_e32 v188, v33, v33
	v_dot2c_f32_bf16_e32 v188, v34, v34
	v_dot2c_f32_bf16_e32 v188, v35, v35
	v_dot2c_f32_bf16_e32 v188, v24, v24
	v_dot2c_f32_bf16_e32 v188, v25, v25
	v_dot2c_f32_bf16_e32 v188, v26, v26
	v_dot2c_f32_bf16_e32 v188, v27, v27
	s_nop 2
	global_store_dword v216, v188, s[88:89] offset:640
	v_mov_b32_e32 v189, 0
	v_dot2c_f32_bf16_e32 v189, v16, v16
	v_dot2c_f32_bf16_e32 v189, v17, v17
	v_dot2c_f32_bf16_e32 v189, v18, v18
	v_dot2c_f32_bf16_e32 v189, v19, v19
	v_dot2c_f32_bf16_e32 v189, v8, v8
	v_dot2c_f32_bf16_e32 v189, v9, v9
	v_dot2c_f32_bf16_e32 v189, v10, v10
	v_dot2c_f32_bf16_e32 v189, v11, v11
	s_nop 2
	global_store_dword v216, v189, s[88:89] offset:704
	s_cbranch_vccz .LBB0_1655
	s_waitcnt vmcnt(0)
	s_cmpk_gt_u32 s2, 0xff
	s_cbranch_scc1 .LBB0_1670
	s_barrier
